# peeled first K iteration (srcC=0, no accumulator zeroing) + layer-0 residual prefetch + attention staging prefetch; baseline priority/barrier order
# speedup vs baseline: 1.0133x; 1.0010x over previous
.LBB0_179:
	s_ashr_i32 s47, s46, 31
	s_lshl_b64 s[48:49], s[46:47], 19
	s_add_u32 s48, s26, s48
	s_addc_u32 s49, s27, s49
	s_and_b64 s[50:51], s[44:45], exec
	s_cselect_b32 s47, s49, s63
	s_cselect_b32 s82, s48, s62
	s_ashr_i32 s21, s20, 31
	s_lshl_b64 s[50:51], s[20:21], 19
	s_add_u32 s50, s59, s50
	s_addc_u32 s51, s66, s51
	s_and_b64 s[84:85], s[44:45], exec
	s_cselect_b32 s21, s51, s61
	s_cselect_b32 s83, s50, s60
	s_add_u32 s89, s60, 0x100
	s_addc_u32 s84, s61, 0
	s_add_u32 s60, s62, 0x40080
	s_addc_u32 s61, s63, 0
	s_mov_b32 s85, -2
	s_add_u32 s62, s60, 0xfffc0080
	s_addc_u32 s63, s61, -1
	s_add_i32 s86, 0, 0x10000
	s_cmp_eq_u32 s85, 12
	s_cselect_b32 vcc_hi, s47, s63
	s_cselect_b32 vcc_lo, s82, s62
	v_add_u32_e32 v142, s86, v145
	s_cselect_b32 s63, s21, s84
	s_cselect_b32 s62, s83, s89
	s_add_i32 s92, 0, 0x14000
	ds_read_b128 v[138:141], v142
	ds_read_b128 v[172:175], v142 offset:1024
	ds_read_b128 v[176:179], v142 offset:2048
	ds_read_b128 v[180:183], v142 offset:3072
	v_add_u32_e32 v142, s92, v145
	ds_read_b128 v[184:187], v142
	ds_read_b128 v[188:191], v142 offset:1024
	ds_read_b128 v[192:195], v142 offset:2048
	ds_read_b128 v[196:199], v142 offset:3072
	v_lshl_add_u64 v[142:143], s[60:61], 0, v[136:137]
	s_add_i32 m0, s68, 0xc000
	ds_read_b128 v[210:213], v148
	ds_read_b128 v[214:217], v148 offset:1024
	ds_read_b128 v[218:221], v148 offset:2048
	ds_read_b128 v[224:227], v148 offset:3072
	ds_read_b128 v[228:231], v148 offset:4096
	ds_read_b128 v[232:235], v148 offset:5120
	ds_read_b128 v[236:239], v148 offset:6144
	ds_read_b128 v[240:243], v148 offset:7168
	global_load_lds_dwordx4 v[142:143], off
	v_lshl_add_u64 v[142:143], s[60:61], 0, v[134:135]
	s_add_i32 m0, s68, 0xe000
	s_nop 0
	global_load_lds_dwordx4 v[142:143], off
	s_waitcnt vmcnt(8)
	s_waitcnt lgkmcnt(0)
	s_barrier
	s_setprio 1
	s_waitcnt lgkmcnt(0)
	v_mfma_f32_16x16x32_bf16 v[124:127], v[138:141], v[210:213], 0
	v_mfma_f32_16x16x32_bf16 v[116:119], v[176:179], v[210:213], 0
	v_mfma_f32_16x16x32_bf16 v[108:111], v[138:141], v[218:221], 0
	v_mfma_f32_16x16x32_bf16 v[100:103], v[176:179], v[218:221], 0
	v_mfma_f32_16x16x32_bf16 v[92:95], v[138:141], v[228:231], 0
	v_mfma_f32_16x16x32_bf16 v[84:87], v[176:179], v[228:231], 0
	v_mfma_f32_16x16x32_bf16 v[76:79], v[138:141], v[236:239], 0
	v_mfma_f32_16x16x32_bf16 v[68:71], v[176:179], v[236:239], 0
	v_mfma_f32_16x16x32_bf16 v[124:127], v[172:175], v[214:217], v[124:127]
	v_mfma_f32_16x16x32_bf16 v[116:119], v[180:183], v[214:217], v[116:119]
	v_mfma_f32_16x16x32_bf16 v[108:111], v[172:175], v[224:227], v[108:111]
	v_mfma_f32_16x16x32_bf16 v[100:103], v[180:183], v[224:227], v[100:103]
	v_mfma_f32_16x16x32_bf16 v[92:95], v[172:175], v[232:235], v[92:95]
	v_mfma_f32_16x16x32_bf16 v[84:87], v[180:183], v[232:235], v[84:87]
	v_mfma_f32_16x16x32_bf16 v[76:79], v[172:175], v[240:243], v[76:79]
	v_mfma_f32_16x16x32_bf16 v[68:71], v[180:183], v[240:243], v[68:71]
	s_setprio 0
	s_setprio 1
	v_mfma_f32_16x16x32_bf16 v[120:123], v[184:187], v[210:213], 0
	v_mfma_f32_16x16x32_bf16 v[112:115], v[192:195], v[210:213], 0
	v_mfma_f32_16x16x32_bf16 v[104:107], v[184:187], v[218:221], 0
	v_mfma_f32_16x16x32_bf16 v[96:99], v[192:195], v[218:221], 0
	v_mfma_f32_16x16x32_bf16 v[88:91], v[184:187], v[228:231], 0
	v_mfma_f32_16x16x32_bf16 v[80:83], v[192:195], v[228:231], 0
	v_mfma_f32_16x16x32_bf16 v[72:75], v[184:187], v[236:239], 0
	v_mfma_f32_16x16x32_bf16 v[64:67], v[192:195], v[236:239], 0
	v_mfma_f32_16x16x32_bf16 v[120:123], v[188:191], v[214:217], v[120:123]
	v_mfma_f32_16x16x32_bf16 v[112:115], v[196:199], v[214:217], v[112:115]
	v_mfma_f32_16x16x32_bf16 v[104:107], v[188:191], v[224:227], v[104:107]
	v_mfma_f32_16x16x32_bf16 v[96:99], v[196:199], v[224:227], v[96:99]
	v_mfma_f32_16x16x32_bf16 v[88:91], v[188:191], v[232:235], v[88:91]
	v_mfma_f32_16x16x32_bf16 v[80:83], v[196:199], v[232:235], v[80:83]
	v_mfma_f32_16x16x32_bf16 v[72:75], v[188:191], v[240:243], v[72:75]
	v_mfma_f32_16x16x32_bf16 v[64:67], v[196:199], v[240:243], v[64:67]
	s_setprio 0
	s_barrier
	s_add_i32 s86, s86, s67
	v_lshl_add_u64 v[142:143], s[62:63], 0, v[152:153]
	s_mov_b32 m0, s86
	ds_read_b128 v[210:213], v148 offset:16384
	ds_read_b128 v[214:217], v148 offset:17408
	ds_read_b128 v[218:221], v148 offset:18432
	ds_read_b128 v[224:227], v148 offset:19456
	ds_read_b128 v[228:231], v148 offset:20480
	ds_read_b128 v[232:235], v148 offset:21504
	ds_read_b128 v[236:239], v148 offset:22528
	ds_read_b128 v[240:243], v148 offset:23552
	global_load_lds_dwordx4 v[142:143], off
	s_add_i32 m0, s86, 0x2000
	s_add_u32 s86, s62, 0x40000
	v_lshl_add_u64 v[150:151], s[62:63], 0, v[128:129]
	s_addc_u32 s87, s63, 0
	s_add_i32 s92, s92, s67
	global_load_lds_dwordx4 v[150:151], off
	v_lshl_add_u64 v[244:245], s[86:87], 0, v[152:153]
	s_mov_b32 m0, s92
	v_lshl_add_u64 v[246:247], vcc, 0, v[130:131]
	global_load_lds_dwordx4 v[244:245], off
	v_lshl_add_u64 v[244:245], s[86:87], 0, v[128:129]
	s_add_i32 m0, s92, 0x2000
	s_nop 0
	global_load_lds_dwordx4 v[244:245], off
	v_lshl_add_u64 v[244:245], vcc, 0, v[132:133]
	s_mov_b32 m0, s68
	s_nop 0
	global_load_lds_dwordx4 v[244:245], off
	s_mov_b32 m0, s69
	s_nop 0
	global_load_lds_dwordx4 v[246:247], off
	s_waitcnt vmcnt(8)
	s_waitcnt lgkmcnt(0)
	s_barrier
	s_setprio 1
	s_waitcnt lgkmcnt(0)
	v_mfma_f32_16x16x32_bf16 v[60:63], v[138:141], v[210:213], 0
	v_mfma_f32_16x16x32_bf16 v[52:55], v[176:179], v[210:213], 0
	v_mfma_f32_16x16x32_bf16 v[44:47], v[138:141], v[218:221], 0
	v_mfma_f32_16x16x32_bf16 v[36:39], v[176:179], v[218:221], 0
	v_mfma_f32_16x16x32_bf16 v[28:31], v[138:141], v[228:231], 0
	v_mfma_f32_16x16x32_bf16 v[20:23], v[176:179], v[228:231], 0
	v_mfma_f32_16x16x32_bf16 v[12:15], v[138:141], v[236:239], 0
	v_mfma_f32_16x16x32_bf16 v[4:7], v[176:179], v[236:239], 0
	v_mfma_f32_16x16x32_bf16 v[60:63], v[172:175], v[214:217], v[60:63]
	v_mfma_f32_16x16x32_bf16 v[52:55], v[180:183], v[214:217], v[52:55]
	v_mfma_f32_16x16x32_bf16 v[44:47], v[172:175], v[224:227], v[44:47]
	v_mfma_f32_16x16x32_bf16 v[36:39], v[180:183], v[224:227], v[36:39]
	v_mfma_f32_16x16x32_bf16 v[28:31], v[172:175], v[232:235], v[28:31]
	v_mfma_f32_16x16x32_bf16 v[20:23], v[180:183], v[232:235], v[20:23]
	v_mfma_f32_16x16x32_bf16 v[12:15], v[172:175], v[240:243], v[12:15]
	v_mfma_f32_16x16x32_bf16 v[4:7], v[180:183], v[240:243], v[4:7]
	s_setprio 0
	s_setprio 1
	v_mfma_f32_16x16x32_bf16 v[56:59], v[184:187], v[210:213], 0
	v_mfma_f32_16x16x32_bf16 v[48:51], v[192:195], v[210:213], 0
	v_mfma_f32_16x16x32_bf16 v[40:43], v[184:187], v[218:221], 0
	v_mfma_f32_16x16x32_bf16 v[32:35], v[192:195], v[218:221], 0
	v_mfma_f32_16x16x32_bf16 v[24:27], v[184:187], v[228:231], 0
	v_mfma_f32_16x16x32_bf16 v[16:19], v[192:195], v[228:231], 0
	v_mfma_f32_16x16x32_bf16 v[8:11], v[184:187], v[236:239], 0
	v_mfma_f32_16x16x32_bf16 v[0:3], v[192:195], v[236:239], 0
	v_mfma_f32_16x16x32_bf16 v[56:59], v[188:191], v[214:217], v[56:59]
	v_mfma_f32_16x16x32_bf16 v[48:51], v[196:199], v[214:217], v[48:51]
	v_mfma_f32_16x16x32_bf16 v[40:43], v[188:191], v[224:227], v[40:43]
	v_mfma_f32_16x16x32_bf16 v[32:35], v[196:199], v[224:227], v[32:35]
	v_mfma_f32_16x16x32_bf16 v[24:27], v[188:191], v[232:235], v[24:27]
	v_mfma_f32_16x16x32_bf16 v[16:19], v[196:199], v[232:235], v[16:19]
	v_mfma_f32_16x16x32_bf16 v[8:11], v[188:191], v[240:243], v[8:11]
	v_mfma_f32_16x16x32_bf16 v[0:3], v[196:199], v[240:243], v[0:3]
	s_setprio 0
	s_barrier
	s_add_i32 s92, 0, 0x18000
	v_add_u32_e32 v149, s92, v145
	s_add_i32 s93, 0, 0x1c000
	ds_read_b128 v[138:141], v149
	ds_read_b128 v[172:175], v149 offset:1024
	ds_read_b128 v[176:179], v149 offset:2048
	ds_read_b128 v[180:183], v149 offset:3072
	v_add_u32_e32 v149, s93, v145
	ds_read_b128 v[184:187], v149
	ds_read_b128 v[188:191], v149 offset:1024
	ds_read_b128 v[192:195], v149 offset:2048
	ds_read_b128 v[196:199], v149 offset:3072
	s_add_u32 s86, vcc_lo, 0x40000
	s_addc_u32 s87, vcc_hi, 0
	s_mov_b32 m0, s74
	v_lshl_add_u64 v[248:249], s[86:87], 0, v[132:133]
	ds_read_b128 v[210:213], v148 offset:32768
	ds_read_b128 v[214:217], v148 offset:33792
	ds_read_b128 v[218:221], v148 offset:34816
	ds_read_b128 v[224:227], v148 offset:35840
	ds_read_b128 v[228:231], v148 offset:36864
	ds_read_b128 v[232:235], v148 offset:37888
	ds_read_b128 v[236:239], v148 offset:38912
	ds_read_b128 v[240:243], v148 offset:39936
	global_load_lds_dwordx4 v[248:249], off
	v_lshl_add_u64 v[248:249], s[86:87], 0, v[130:131]
	s_mov_b32 m0, s75
	s_nop 0
	global_load_lds_dwordx4 v[248:249], off
	s_waitcnt vmcnt(8)
	s_waitcnt lgkmcnt(0)
	s_barrier
	s_setprio 1
	s_waitcnt lgkmcnt(0)
	v_mfma_f32_16x16x32_bf16 v[124:127], v[138:141], v[210:213], v[124:127]
	v_mfma_f32_16x16x32_bf16 v[116:119], v[176:179], v[210:213], v[116:119]
	v_mfma_f32_16x16x32_bf16 v[108:111], v[138:141], v[218:221], v[108:111]
	v_mfma_f32_16x16x32_bf16 v[100:103], v[176:179], v[218:221], v[100:103]
	v_mfma_f32_16x16x32_bf16 v[92:95], v[138:141], v[228:231], v[92:95]
	v_mfma_f32_16x16x32_bf16 v[84:87], v[176:179], v[228:231], v[84:87]
	v_mfma_f32_16x16x32_bf16 v[76:79], v[138:141], v[236:239], v[76:79]
	v_mfma_f32_16x16x32_bf16 v[68:71], v[176:179], v[236:239], v[68:71]
	v_mfma_f32_16x16x32_bf16 v[124:127], v[172:175], v[214:217], v[124:127]
	v_mfma_f32_16x16x32_bf16 v[116:119], v[180:183], v[214:217], v[116:119]
	v_mfma_f32_16x16x32_bf16 v[108:111], v[172:175], v[224:227], v[108:111]
	v_mfma_f32_16x16x32_bf16 v[100:103], v[180:183], v[224:227], v[100:103]
	v_mfma_f32_16x16x32_bf16 v[92:95], v[172:175], v[232:235], v[92:95]
	v_mfma_f32_16x16x32_bf16 v[84:87], v[180:183], v[232:235], v[84:87]
	v_mfma_f32_16x16x32_bf16 v[76:79], v[172:175], v[240:243], v[76:79]
	v_mfma_f32_16x16x32_bf16 v[68:71], v[180:183], v[240:243], v[68:71]
	s_setprio 0
	s_setprio 1
	v_mfma_f32_16x16x32_bf16 v[120:123], v[184:187], v[210:213], v[120:123]
	v_mfma_f32_16x16x32_bf16 v[112:115], v[192:195], v[210:213], v[112:115]
	v_mfma_f32_16x16x32_bf16 v[104:107], v[184:187], v[218:221], v[104:107]
	v_mfma_f32_16x16x32_bf16 v[96:99], v[192:195], v[218:221], v[96:99]
	v_mfma_f32_16x16x32_bf16 v[88:91], v[184:187], v[228:231], v[88:91]
	v_mfma_f32_16x16x32_bf16 v[80:83], v[192:195], v[228:231], v[80:83]
	v_mfma_f32_16x16x32_bf16 v[72:75], v[184:187], v[236:239], v[72:75]
	v_mfma_f32_16x16x32_bf16 v[64:67], v[192:195], v[236:239], v[64:67]
	v_mfma_f32_16x16x32_bf16 v[120:123], v[188:191], v[214:217], v[120:123]
	v_mfma_f32_16x16x32_bf16 v[112:115], v[196:199], v[214:217], v[112:115]
	v_mfma_f32_16x16x32_bf16 v[104:107], v[188:191], v[224:227], v[104:107]
	v_mfma_f32_16x16x32_bf16 v[96:99], v[196:199], v[224:227], v[96:99]
	v_mfma_f32_16x16x32_bf16 v[88:91], v[188:191], v[232:235], v[88:91]
	v_mfma_f32_16x16x32_bf16 v[80:83], v[196:199], v[232:235], v[80:83]
	v_mfma_f32_16x16x32_bf16 v[72:75], v[188:191], v[240:243], v[72:75]
	v_mfma_f32_16x16x32_bf16 v[64:67], v[196:199], v[240:243], v[64:67]
	s_setprio 0
	s_barrier
	s_add_i32 s86, s92, s67
	v_lshl_add_u64 v[142:143], v[142:143], 0, s[22:23]
	s_mov_b32 m0, s86
	ds_read_b128 v[210:213], v148 offset:49152
	ds_read_b128 v[214:217], v148 offset:50176
	ds_read_b128 v[218:221], v148 offset:51200
	ds_read_b128 v[224:227], v148 offset:52224
	ds_read_b128 v[228:231], v148 offset:53248
	ds_read_b128 v[232:235], v148 offset:54272
	ds_read_b128 v[236:239], v148 offset:55296
	ds_read_b128 v[240:243], v148 offset:56320
	global_load_lds_dwordx4 v[142:143], off
	s_add_i32 m0, s86, 0x2000
	s_add_u32 s62, s62, 0x40080
	v_lshl_add_u64 v[142:143], v[150:151], 0, s[22:23]
	s_addc_u32 s63, s63, 0
	s_add_i32 s86, s93, s67
	global_load_lds_dwordx4 v[142:143], off
	v_lshl_add_u64 v[142:143], s[62:63], 0, v[152:153]
	s_mov_b32 m0, s86
	s_nop 0
	global_load_lds_dwordx4 v[142:143], off
	v_lshl_add_u64 v[142:143], s[62:63], 0, v[128:129]
	s_add_i32 m0, s86, 0x2000
	s_nop 0
	global_load_lds_dwordx4 v[142:143], off
	v_lshl_add_u64 v[142:143], v[244:245], 0, s[22:23]
	s_mov_b32 m0, s77
	s_nop 0
	global_load_lds_dwordx4 v[142:143], off
	v_lshl_add_u64 v[142:143], v[246:247], 0, s[22:23]
	s_mov_b32 m0, s78
	s_nop 0
	global_load_lds_dwordx4 v[142:143], off
	s_waitcnt vmcnt(8)
	s_waitcnt lgkmcnt(0)
	s_barrier
	s_setprio 1
	s_waitcnt lgkmcnt(0)
	v_mfma_f32_16x16x32_bf16 v[60:63], v[138:141], v[210:213], v[60:63]
	v_mfma_f32_16x16x32_bf16 v[52:55], v[176:179], v[210:213], v[52:55]
	v_mfma_f32_16x16x32_bf16 v[44:47], v[138:141], v[218:221], v[44:47]
	v_mfma_f32_16x16x32_bf16 v[36:39], v[176:179], v[218:221], v[36:39]
	v_mfma_f32_16x16x32_bf16 v[28:31], v[138:141], v[228:231], v[28:31]
	v_mfma_f32_16x16x32_bf16 v[20:23], v[176:179], v[228:231], v[20:23]
	v_mfma_f32_16x16x32_bf16 v[12:15], v[138:141], v[236:239], v[12:15]
	v_mfma_f32_16x16x32_bf16 v[4:7], v[176:179], v[236:239], v[4:7]
	v_mfma_f32_16x16x32_bf16 v[60:63], v[172:175], v[214:217], v[60:63]
	v_mfma_f32_16x16x32_bf16 v[52:55], v[180:183], v[214:217], v[52:55]
	v_mfma_f32_16x16x32_bf16 v[44:47], v[172:175], v[224:227], v[44:47]
	v_mfma_f32_16x16x32_bf16 v[36:39], v[180:183], v[224:227], v[36:39]
	v_mfma_f32_16x16x32_bf16 v[28:31], v[172:175], v[232:235], v[28:31]
	v_mfma_f32_16x16x32_bf16 v[20:23], v[180:183], v[232:235], v[20:23]
	v_mfma_f32_16x16x32_bf16 v[12:15], v[172:175], v[240:243], v[12:15]
	v_mfma_f32_16x16x32_bf16 v[4:7], v[180:183], v[240:243], v[4:7]
	s_setprio 0
	s_setprio 1
	v_mfma_f32_16x16x32_bf16 v[56:59], v[184:187], v[210:213], v[56:59]
	v_mfma_f32_16x16x32_bf16 v[48:51], v[192:195], v[210:213], v[48:51]
	v_mfma_f32_16x16x32_bf16 v[40:43], v[184:187], v[218:221], v[40:43]
	v_mfma_f32_16x16x32_bf16 v[32:35], v[192:195], v[218:221], v[32:35]
	v_mfma_f32_16x16x32_bf16 v[24:27], v[184:187], v[228:231], v[24:27]
	v_mfma_f32_16x16x32_bf16 v[16:19], v[192:195], v[228:231], v[16:19]
	v_mfma_f32_16x16x32_bf16 v[8:11], v[184:187], v[236:239], v[8:11]
	v_mfma_f32_16x16x32_bf16 v[0:3], v[192:195], v[236:239], v[0:3]
	v_mfma_f32_16x16x32_bf16 v[56:59], v[188:191], v[214:217], v[56:59]
	v_mfma_f32_16x16x32_bf16 v[48:51], v[196:199], v[214:217], v[48:51]
	v_mfma_f32_16x16x32_bf16 v[40:43], v[188:191], v[224:227], v[40:43]
	v_mfma_f32_16x16x32_bf16 v[32:35], v[196:199], v[224:227], v[32:35]
	v_mfma_f32_16x16x32_bf16 v[24:27], v[188:191], v[232:235], v[24:27]
	v_mfma_f32_16x16x32_bf16 v[16:19], v[196:199], v[232:235], v[16:19]
	v_mfma_f32_16x16x32_bf16 v[8:11], v[188:191], v[240:243], v[8:11]
	v_mfma_f32_16x16x32_bf16 v[0:3], v[196:199], v[240:243], v[0:3]
	s_setprio 0
	s_barrier
	s_add_i32 s85, s85, 2
	s_add_u32 s89, s89, 0x100
	s_addc_u32 s84, s84, 0
	s_add_u32 s60, s60, 0x100
	s_addc_u32 s61, s61, 0
	s_cmp_gt_u32 s85, 13

.LBB0_280:
	s_add_u32 s84, s18, 0x100
	s_addc_u32 s85, s19, 0
	s_mov_b32 s86, -2
	s_waitcnt lgkmcnt(0)
	s_add_u32 vcc_lo, s60, 0x100
	s_addc_u32 vcc_hi, s61, 0
	s_add_i32 s87, 0, 0x10000
	s_cmp_eq_u32 s86, 40
	s_cselect_b32 s67, s51, vcc_hi
	s_cselect_b32 s66, s50, vcc_lo
	s_cselect_b32 s19, s45, s85
	s_cselect_b32 s18, s44, s84
	s_add_i32 s92, 0, 0x14000
	v_add_u32_e32 v140, s87, v210
	v_add_u32_e32 v186, s92, v210
	ds_read_b128 v[128:131], v140
	ds_read_b128 v[132:135], v140 offset:1024
	ds_read_b128 v[136:139], v140 offset:2048
	ds_read_b128 v[140:143], v140 offset:3072
	ds_read_b128 v[144:147], v186
	ds_read_b128 v[148:151], v186 offset:1024
	ds_read_b128 v[182:185], v186 offset:2048
	ds_read_b128 v[186:189], v186 offset:3072
	v_lshl_add_u64 v[198:199], s[60:61], 0, v[180:181]
	s_add_i32 m0, s69, 0xc000
	ds_read_b128 v[190:193], v212
	ds_read_b128 v[194:197], v212 offset:1024
	ds_read_b128 v[214:217], v212 offset:2048
	ds_read_b128 v[218:221], v212 offset:3072
	ds_read_b128 v[224:227], v212 offset:4096
	ds_read_b128 v[228:231], v212 offset:5120
	ds_read_b128 v[232:235], v212 offset:6144
	ds_read_b128 v[236:239], v212 offset:7168
	global_load_lds_dwordx4 v[198:199], off
	v_lshl_add_u64 v[198:199], s[60:61], 0, v[178:179]
	s_add_i32 m0, s69, 0xe000
	s_nop 0
	global_load_lds_dwordx4 v[198:199], off
	s_waitcnt vmcnt(8)
	s_waitcnt lgkmcnt(0)
	s_barrier
	s_setprio 1
	s_waitcnt lgkmcnt(0)
	v_mfma_f32_16x16x32_bf16 v[124:127], v[128:131], v[190:193], 0
	v_mfma_f32_16x16x32_bf16 v[120:123], v[136:139], v[190:193], 0
	v_mfma_f32_16x16x32_bf16 v[108:111], v[128:131], v[214:217], 0
	v_mfma_f32_16x16x32_bf16 v[104:107], v[136:139], v[214:217], 0
	v_mfma_f32_16x16x32_bf16 v[92:95], v[128:131], v[224:227], 0
	v_mfma_f32_16x16x32_bf16 v[88:91], v[136:139], v[224:227], 0
	v_mfma_f32_16x16x32_bf16 v[76:79], v[128:131], v[232:235], 0
	v_mfma_f32_16x16x32_bf16 v[72:75], v[136:139], v[232:235], 0
	v_mfma_f32_16x16x32_bf16 v[124:127], v[132:135], v[194:197], v[124:127]
	v_mfma_f32_16x16x32_bf16 v[120:123], v[140:143], v[194:197], v[120:123]
	v_mfma_f32_16x16x32_bf16 v[108:111], v[132:135], v[218:221], v[108:111]
	v_mfma_f32_16x16x32_bf16 v[104:107], v[140:143], v[218:221], v[104:107]
	v_mfma_f32_16x16x32_bf16 v[92:95], v[132:135], v[228:231], v[92:95]
	v_mfma_f32_16x16x32_bf16 v[88:91], v[140:143], v[228:231], v[88:91]
	v_mfma_f32_16x16x32_bf16 v[76:79], v[132:135], v[236:239], v[76:79]
	v_mfma_f32_16x16x32_bf16 v[72:75], v[140:143], v[236:239], v[72:75]
	s_setprio 0
	s_setprio 1
	v_mfma_f32_16x16x32_bf16 v[116:119], v[144:147], v[190:193], 0
	v_mfma_f32_16x16x32_bf16 v[112:115], v[182:185], v[190:193], 0
	v_mfma_f32_16x16x32_bf16 v[100:103], v[144:147], v[214:217], 0
	v_mfma_f32_16x16x32_bf16 v[96:99], v[182:185], v[214:217], 0
	v_mfma_f32_16x16x32_bf16 v[84:87], v[144:147], v[224:227], 0
	v_mfma_f32_16x16x32_bf16 v[80:83], v[182:185], v[224:227], 0
	v_mfma_f32_16x16x32_bf16 v[68:71], v[144:147], v[232:235], 0
	v_mfma_f32_16x16x32_bf16 v[64:67], v[182:185], v[232:235], 0
	v_mfma_f32_16x16x32_bf16 v[116:119], v[148:151], v[194:197], v[116:119]
	v_mfma_f32_16x16x32_bf16 v[112:115], v[186:189], v[194:197], v[112:115]
	v_mfma_f32_16x16x32_bf16 v[100:103], v[148:151], v[218:221], v[100:103]
	v_mfma_f32_16x16x32_bf16 v[96:99], v[186:189], v[218:221], v[96:99]
	v_mfma_f32_16x16x32_bf16 v[84:87], v[148:151], v[228:231], v[84:87]
	v_mfma_f32_16x16x32_bf16 v[80:83], v[186:189], v[228:231], v[80:83]
	v_mfma_f32_16x16x32_bf16 v[68:71], v[148:151], v[236:239], v[68:71]
	v_mfma_f32_16x16x32_bf16 v[64:67], v[186:189], v[236:239], v[64:67]
	s_setprio 0
	s_barrier
	s_add_i32 s60, s87, s68
	v_lshl_add_u64 v[198:199], s[18:19], 0, v[152:153]
	s_mov_b32 m0, s60
	ds_read_b128 v[190:193], v212 offset:16384
	ds_read_b128 v[194:197], v212 offset:17408
	ds_read_b128 v[214:217], v212 offset:18432
	ds_read_b128 v[218:221], v212 offset:19456
	ds_read_b128 v[224:227], v212 offset:20480
	ds_read_b128 v[228:231], v212 offset:21504
	ds_read_b128 v[232:235], v212 offset:22528
	ds_read_b128 v[236:239], v212 offset:23552
	global_load_lds_dwordx4 v[198:199], off
	s_add_i32 m0, s60, 0x2000
	s_add_u32 s60, s18, 0xb0000
	v_lshl_add_u64 v[240:241], s[18:19], 0, v[172:173]
	s_addc_u32 s61, s19, 0
	s_add_i32 s87, s92, s68
	global_load_lds_dwordx4 v[240:241], off
	v_lshl_add_u64 v[242:243], s[60:61], 0, v[152:153]
	s_mov_b32 m0, s87
	v_lshl_add_u64 v[244:245], s[66:67], 0, v[174:175]
	global_load_lds_dwordx4 v[242:243], off
	v_lshl_add_u64 v[242:243], s[60:61], 0, v[172:173]
	s_add_i32 m0, s87, 0x2000
	s_nop 0
	global_load_lds_dwordx4 v[242:243], off
	v_lshl_add_u64 v[242:243], s[66:67], 0, v[176:177]
	s_mov_b32 m0, s69
	s_nop 0
	global_load_lds_dwordx4 v[242:243], off
	s_mov_b32 m0, s74
	s_nop 0
	global_load_lds_dwordx4 v[244:245], off
	s_waitcnt vmcnt(8)
	s_waitcnt lgkmcnt(0)
	s_barrier
	s_setprio 1
	s_waitcnt lgkmcnt(0)
	v_mfma_f32_16x16x32_bf16 v[60:63], v[128:131], v[190:193], 0
	v_mfma_f32_16x16x32_bf16 v[56:59], v[136:139], v[190:193], 0
	v_mfma_f32_16x16x32_bf16 v[44:47], v[128:131], v[214:217], 0
	v_mfma_f32_16x16x32_bf16 v[40:43], v[136:139], v[214:217], 0
	v_mfma_f32_16x16x32_bf16 v[28:31], v[128:131], v[224:227], 0
	v_mfma_f32_16x16x32_bf16 v[24:27], v[136:139], v[224:227], 0
	v_mfma_f32_16x16x32_bf16 v[12:15], v[128:131], v[232:235], 0
	v_mfma_f32_16x16x32_bf16 v[8:11], v[136:139], v[232:235], 0
	v_mfma_f32_16x16x32_bf16 v[60:63], v[132:135], v[194:197], v[60:63]
	v_mfma_f32_16x16x32_bf16 v[56:59], v[140:143], v[194:197], v[56:59]
	v_mfma_f32_16x16x32_bf16 v[44:47], v[132:135], v[218:221], v[44:47]
	v_mfma_f32_16x16x32_bf16 v[40:43], v[140:143], v[218:221], v[40:43]
	v_mfma_f32_16x16x32_bf16 v[28:31], v[132:135], v[228:231], v[28:31]
	v_mfma_f32_16x16x32_bf16 v[24:27], v[140:143], v[228:231], v[24:27]
	v_mfma_f32_16x16x32_bf16 v[12:15], v[132:135], v[236:239], v[12:15]
	v_mfma_f32_16x16x32_bf16 v[8:11], v[140:143], v[236:239], v[8:11]
	s_setprio 0
	s_setprio 1
	v_mfma_f32_16x16x32_bf16 v[52:55], v[144:147], v[190:193], 0
	v_mfma_f32_16x16x32_bf16 v[48:51], v[182:185], v[190:193], 0
	v_mfma_f32_16x16x32_bf16 v[36:39], v[144:147], v[214:217], 0
	v_mfma_f32_16x16x32_bf16 v[32:35], v[182:185], v[214:217], 0
	v_mfma_f32_16x16x32_bf16 v[20:23], v[144:147], v[224:227], 0
	v_mfma_f32_16x16x32_bf16 v[16:19], v[182:185], v[224:227], 0
	v_mfma_f32_16x16x32_bf16 v[4:7], v[144:147], v[232:235], 0
	v_mfma_f32_16x16x32_bf16 v[0:3], v[182:185], v[232:235], 0
	v_mfma_f32_16x16x32_bf16 v[52:55], v[148:151], v[194:197], v[52:55]
	v_mfma_f32_16x16x32_bf16 v[48:51], v[186:189], v[194:197], v[48:51]
	v_mfma_f32_16x16x32_bf16 v[36:39], v[148:151], v[218:221], v[36:39]
	v_mfma_f32_16x16x32_bf16 v[32:35], v[186:189], v[218:221], v[32:35]
	v_mfma_f32_16x16x32_bf16 v[20:23], v[148:151], v[228:231], v[20:23]
	v_mfma_f32_16x16x32_bf16 v[16:19], v[186:189], v[228:231], v[16:19]
	v_mfma_f32_16x16x32_bf16 v[4:7], v[148:151], v[236:239], v[4:7]
	v_mfma_f32_16x16x32_bf16 v[0:3], v[186:189], v[236:239], v[0:3]
	s_setprio 0
	s_barrier
	s_add_i32 s87, 0, 0x18000
	s_add_i32 s92, 0, 0x1c000
	v_add_u32_e32 v140, s87, v210
	v_add_u32_e32 v186, s92, v210
	ds_read_b128 v[128:131], v140
	ds_read_b128 v[132:135], v140 offset:1024
	ds_read_b128 v[136:139], v140 offset:2048
	ds_read_b128 v[140:143], v140 offset:3072
	ds_read_b128 v[144:147], v186
	ds_read_b128 v[148:151], v186 offset:1024
	ds_read_b128 v[182:185], v186 offset:2048
	ds_read_b128 v[186:189], v186 offset:3072
	s_add_u32 s60, s66, 0xb0000
	s_addc_u32 s61, s67, 0
	s_mov_b32 m0, s75
	v_lshl_add_u64 v[246:247], s[60:61], 0, v[176:177]
	ds_read_b128 v[190:193], v212 offset:32768
	ds_read_b128 v[194:197], v212 offset:33792
	ds_read_b128 v[214:217], v212 offset:34816
	ds_read_b128 v[218:221], v212 offset:35840
	ds_read_b128 v[224:227], v212 offset:36864
	ds_read_b128 v[228:231], v212 offset:37888
	ds_read_b128 v[232:235], v212 offset:38912
	ds_read_b128 v[236:239], v212 offset:39936
	global_load_lds_dwordx4 v[246:247], off
	v_lshl_add_u64 v[246:247], s[60:61], 0, v[174:175]
	s_mov_b32 m0, s76
	s_nop 0
	global_load_lds_dwordx4 v[246:247], off
	s_waitcnt vmcnt(8)
	s_waitcnt lgkmcnt(0)
	s_barrier
	s_setprio 1
	s_waitcnt lgkmcnt(0)
	v_mfma_f32_16x16x32_bf16 v[124:127], v[128:131], v[190:193], v[124:127]
	v_mfma_f32_16x16x32_bf16 v[120:123], v[136:139], v[190:193], v[120:123]
	v_mfma_f32_16x16x32_bf16 v[108:111], v[128:131], v[214:217], v[108:111]
	v_mfma_f32_16x16x32_bf16 v[104:107], v[136:139], v[214:217], v[104:107]
	v_mfma_f32_16x16x32_bf16 v[92:95], v[128:131], v[224:227], v[92:95]
	v_mfma_f32_16x16x32_bf16 v[88:91], v[136:139], v[224:227], v[88:91]
	v_mfma_f32_16x16x32_bf16 v[76:79], v[128:131], v[232:235], v[76:79]
	v_mfma_f32_16x16x32_bf16 v[72:75], v[136:139], v[232:235], v[72:75]
	v_mfma_f32_16x16x32_bf16 v[124:127], v[132:135], v[194:197], v[124:127]
	v_mfma_f32_16x16x32_bf16 v[120:123], v[140:143], v[194:197], v[120:123]
	v_mfma_f32_16x16x32_bf16 v[108:111], v[132:135], v[218:221], v[108:111]
	v_mfma_f32_16x16x32_bf16 v[104:107], v[140:143], v[218:221], v[104:107]
	v_mfma_f32_16x16x32_bf16 v[92:95], v[132:135], v[228:231], v[92:95]
	v_mfma_f32_16x16x32_bf16 v[88:91], v[140:143], v[228:231], v[88:91]
	v_mfma_f32_16x16x32_bf16 v[76:79], v[132:135], v[236:239], v[76:79]
	v_mfma_f32_16x16x32_bf16 v[72:75], v[140:143], v[236:239], v[72:75]
	s_setprio 0
	s_setprio 1
	v_mfma_f32_16x16x32_bf16 v[116:119], v[144:147], v[190:193], v[116:119]
	v_mfma_f32_16x16x32_bf16 v[112:115], v[182:185], v[190:193], v[112:115]
	v_mfma_f32_16x16x32_bf16 v[100:103], v[144:147], v[214:217], v[100:103]
	v_mfma_f32_16x16x32_bf16 v[96:99], v[182:185], v[214:217], v[96:99]
	v_mfma_f32_16x16x32_bf16 v[84:87], v[144:147], v[224:227], v[84:87]
	v_mfma_f32_16x16x32_bf16 v[80:83], v[182:185], v[224:227], v[80:83]
	v_mfma_f32_16x16x32_bf16 v[68:71], v[144:147], v[232:235], v[68:71]
	v_mfma_f32_16x16x32_bf16 v[64:67], v[182:185], v[232:235], v[64:67]
	v_mfma_f32_16x16x32_bf16 v[116:119], v[148:151], v[194:197], v[116:119]
	v_mfma_f32_16x16x32_bf16 v[112:115], v[186:189], v[194:197], v[112:115]
	v_mfma_f32_16x16x32_bf16 v[100:103], v[148:151], v[218:221], v[100:103]
	v_mfma_f32_16x16x32_bf16 v[96:99], v[186:189], v[218:221], v[96:99]
	v_mfma_f32_16x16x32_bf16 v[84:87], v[148:151], v[228:231], v[84:87]
	v_mfma_f32_16x16x32_bf16 v[80:83], v[186:189], v[228:231], v[80:83]
	v_mfma_f32_16x16x32_bf16 v[68:71], v[148:151], v[236:239], v[68:71]
	v_mfma_f32_16x16x32_bf16 v[64:67], v[186:189], v[236:239], v[64:67]
	s_setprio 0
	s_barrier
	s_add_i32 s60, s87, s68
	v_lshl_add_u64 v[198:199], v[198:199], 0, s[22:23]
	s_mov_b32 m0, s60
	ds_read_b128 v[190:193], v212 offset:49152
	ds_read_b128 v[194:197], v212 offset:50176
	ds_read_b128 v[214:217], v212 offset:51200
	ds_read_b128 v[218:221], v212 offset:52224
	ds_read_b128 v[224:227], v212 offset:53248
	ds_read_b128 v[228:231], v212 offset:54272
	ds_read_b128 v[232:235], v212 offset:55296
	ds_read_b128 v[236:239], v212 offset:56320
	global_load_lds_dwordx4 v[198:199], off
	s_add_i32 m0, s60, 0x2000
	s_add_u32 s18, s18, 0xb0080
	v_lshl_add_u64 v[198:199], v[240:241], 0, s[22:23]
	s_addc_u32 s19, s19, 0
	s_add_i32 s60, s92, s68
	global_load_lds_dwordx4 v[198:199], off
	v_lshl_add_u64 v[198:199], s[18:19], 0, v[152:153]
	s_mov_b32 m0, s60
	s_nop 0
	global_load_lds_dwordx4 v[198:199], off
	v_lshl_add_u64 v[198:199], s[18:19], 0, v[172:173]
	s_add_i32 m0, s60, 0x2000
	s_nop 0
	global_load_lds_dwordx4 v[198:199], off
	v_lshl_add_u64 v[198:199], v[242:243], 0, s[22:23]
	s_mov_b32 m0, s79
	s_nop 0
	global_load_lds_dwordx4 v[198:199], off
	v_lshl_add_u64 v[198:199], v[244:245], 0, s[22:23]
	s_mov_b32 m0, s80
	s_nop 0
	global_load_lds_dwordx4 v[198:199], off
	s_waitcnt vmcnt(8)
	s_waitcnt lgkmcnt(0)
	s_barrier
	s_setprio 1
	s_waitcnt lgkmcnt(0)
	v_mfma_f32_16x16x32_bf16 v[60:63], v[128:131], v[190:193], v[60:63]
	v_mfma_f32_16x16x32_bf16 v[56:59], v[136:139], v[190:193], v[56:59]
	v_mfma_f32_16x16x32_bf16 v[44:47], v[128:131], v[214:217], v[44:47]
	v_mfma_f32_16x16x32_bf16 v[40:43], v[136:139], v[214:217], v[40:43]
	v_mfma_f32_16x16x32_bf16 v[28:31], v[128:131], v[224:227], v[28:31]
	v_mfma_f32_16x16x32_bf16 v[24:27], v[136:139], v[224:227], v[24:27]
	v_mfma_f32_16x16x32_bf16 v[12:15], v[128:131], v[232:235], v[12:15]
	v_mfma_f32_16x16x32_bf16 v[8:11], v[136:139], v[232:235], v[8:11]
	v_mfma_f32_16x16x32_bf16 v[60:63], v[132:135], v[194:197], v[60:63]
	v_mfma_f32_16x16x32_bf16 v[56:59], v[140:143], v[194:197], v[56:59]
	v_mfma_f32_16x16x32_bf16 v[44:47], v[132:135], v[218:221], v[44:47]
	v_mfma_f32_16x16x32_bf16 v[40:43], v[140:143], v[218:221], v[40:43]
	v_mfma_f32_16x16x32_bf16 v[28:31], v[132:135], v[228:231], v[28:31]
	v_mfma_f32_16x16x32_bf16 v[24:27], v[140:143], v[228:231], v[24:27]
	v_mfma_f32_16x16x32_bf16 v[12:15], v[132:135], v[236:239], v[12:15]
	v_mfma_f32_16x16x32_bf16 v[8:11], v[140:143], v[236:239], v[8:11]
	s_setprio 0
	s_setprio 1
	v_mfma_f32_16x16x32_bf16 v[52:55], v[144:147], v[190:193], v[52:55]
	v_mfma_f32_16x16x32_bf16 v[48:51], v[182:185], v[190:193], v[48:51]
	v_mfma_f32_16x16x32_bf16 v[36:39], v[144:147], v[214:217], v[36:39]
	v_mfma_f32_16x16x32_bf16 v[32:35], v[182:185], v[214:217], v[32:35]
	v_mfma_f32_16x16x32_bf16 v[20:23], v[144:147], v[224:227], v[20:23]
	v_mfma_f32_16x16x32_bf16 v[16:19], v[182:185], v[224:227], v[16:19]
	v_mfma_f32_16x16x32_bf16 v[4:7], v[144:147], v[232:235], v[4:7]
	v_mfma_f32_16x16x32_bf16 v[0:3], v[182:185], v[232:235], v[0:3]
	v_mfma_f32_16x16x32_bf16 v[52:55], v[148:151], v[194:197], v[52:55]
	v_mfma_f32_16x16x32_bf16 v[48:51], v[186:189], v[194:197], v[48:51]
	v_mfma_f32_16x16x32_bf16 v[36:39], v[148:151], v[218:221], v[36:39]
	v_mfma_f32_16x16x32_bf16 v[32:35], v[186:189], v[218:221], v[32:35]
	v_mfma_f32_16x16x32_bf16 v[20:23], v[148:151], v[228:231], v[20:23]
	v_mfma_f32_16x16x32_bf16 v[16:19], v[186:189], v[228:231], v[16:19]
	v_mfma_f32_16x16x32_bf16 v[4:7], v[148:151], v[236:239], v[4:7]
	v_mfma_f32_16x16x32_bf16 v[0:3], v[186:189], v[236:239], v[0:3]
	s_setprio 0
	s_barrier
	s_add_i32 s86, s86, 2
	s_add_u32 s84, s84, 0x100
	s_addc_u32 s85, s85, 0
	s_cmp_gt_u32 s86, 41
	s_mov_b64 s[60:61], vcc

.LBB0_418:
	s_ashr_i32 s21, s20, 31
	s_lshl_b64 s[50:51], s[20:21], 19
	s_add_u32 s50, s26, s50
	s_addc_u32 s51, s27, s51
	s_and_b64 s[60:61], s[46:47], exec
	s_cselect_b32 s21, s51, s45
	s_cselect_b32 s78, s50, s44
	s_ashr_i32 s19, s18, 31
	s_lshl_b64 s[60:61], s[18:19], 19
	v_readlane_b32 s19, v254, 42
	s_add_u32 s60, s19, s60
	v_readlane_b32 s19, v254, 43
	s_addc_u32 s61, s19, s61
	s_and_b64 s[62:63], s[46:47], exec
	s_cselect_b32 s19, s61, s49
	s_cselect_b32 s79, s60, s48
	s_add_u32 s80, s48, 0x100
	s_addc_u32 s81, s49, 0
	s_add_u32 s48, s44, 0x40080
	s_addc_u32 s49, s45, 0
	s_mov_b32 s82, -2
	s_add_u32 s44, s48, 0xfffc0080
	s_addc_u32 s45, s49, -1
	s_add_i32 s83, 0, 0x10000
	s_cmp_eq_u32 s82, 12
	s_cselect_b32 s63, s21, s45
	s_cselect_b32 s62, s78, s44
	s_cselect_b32 s45, s19, s81
	s_cselect_b32 s44, s79, s80
	s_add_i32 s86, 0, 0x14000
	v_add_u32_e32 v88, s83, v185
	v_add_u32_e32 v182, s86, v185
	ds_read_b128 v[72:75], v88
	ds_read_b128 v[76:79], v88 offset:1024
	ds_read_b128 v[80:83], v88 offset:2048
	ds_read_b128 v[88:91], v88 offset:3072
	ds_read_b128 v[174:177], v182
	ds_read_b128 v[178:181], v182 offset:1024
	ds_read_b128 v[190:193], v182 offset:2048
	ds_read_b128 v[194:197], v182 offset:3072
	v_lshl_add_u64 v[182:183], s[48:49], 0, v[172:173]
	s_add_i32 m0, s59, 0xc000
	ds_read_b128 v[210:213], v188
	ds_read_b128 v[214:217], v188 offset:1024
	ds_read_b128 v[218:221], v188 offset:2048
	ds_read_b128 v[224:227], v188 offset:3072
	ds_read_b128 v[228:231], v188 offset:4096
	ds_read_b128 v[232:235], v188 offset:5120
	ds_read_b128 v[236:239], v188 offset:6144
	ds_read_b128 v[240:243], v188 offset:7168
	global_load_lds_dwordx4 v[182:183], off
	v_lshl_add_u64 v[182:183], s[48:49], 0, v[150:151]
	s_add_i32 m0, s59, 0xe000
	s_nop 0
	global_load_lds_dwordx4 v[182:183], off
	s_waitcnt vmcnt(8)
	s_waitcnt lgkmcnt(0)
	s_barrier
	s_setprio 1
	s_waitcnt lgkmcnt(0)
	v_mfma_f32_16x16x32_bf16 v[140:143], v[72:75], v[210:213], 0
	v_mfma_f32_16x16x32_bf16 v[136:139], v[80:83], v[210:213], 0
	v_mfma_f32_16x16x32_bf16 v[124:127], v[72:75], v[218:221], 0
	v_mfma_f32_16x16x32_bf16 v[120:123], v[80:83], v[218:221], 0
	v_mfma_f32_16x16x32_bf16 v[108:111], v[72:75], v[228:231], 0
	v_mfma_f32_16x16x32_bf16 v[104:107], v[80:83], v[228:231], 0
	v_mfma_f32_16x16x32_bf16 v[92:95], v[72:75], v[236:239], 0
	v_mfma_f32_16x16x32_bf16 v[84:87], v[80:83], v[236:239], 0
	v_mfma_f32_16x16x32_bf16 v[140:143], v[76:79], v[214:217], v[140:143]
	v_mfma_f32_16x16x32_bf16 v[136:139], v[88:91], v[214:217], v[136:139]
	v_mfma_f32_16x16x32_bf16 v[124:127], v[76:79], v[224:227], v[124:127]
	v_mfma_f32_16x16x32_bf16 v[120:123], v[88:91], v[224:227], v[120:123]
	v_mfma_f32_16x16x32_bf16 v[108:111], v[76:79], v[232:235], v[108:111]
	v_mfma_f32_16x16x32_bf16 v[104:107], v[88:91], v[232:235], v[104:107]
	v_mfma_f32_16x16x32_bf16 v[92:95], v[76:79], v[240:243], v[92:95]
	v_mfma_f32_16x16x32_bf16 v[84:87], v[88:91], v[240:243], v[84:87]
	s_setprio 0
	s_setprio 1
	v_mfma_f32_16x16x32_bf16 v[132:135], v[174:177], v[210:213], 0
	v_mfma_f32_16x16x32_bf16 v[128:131], v[190:193], v[210:213], 0
	v_mfma_f32_16x16x32_bf16 v[116:119], v[174:177], v[218:221], 0
	v_mfma_f32_16x16x32_bf16 v[112:115], v[190:193], v[218:221], 0
	v_mfma_f32_16x16x32_bf16 v[100:103], v[174:177], v[228:231], 0
	v_mfma_f32_16x16x32_bf16 v[96:99], v[190:193], v[228:231], 0
	v_mfma_f32_16x16x32_bf16 v[68:71], v[174:177], v[236:239], 0
	v_mfma_f32_16x16x32_bf16 v[64:67], v[190:193], v[236:239], 0
	v_mfma_f32_16x16x32_bf16 v[132:135], v[178:181], v[214:217], v[132:135]
	v_mfma_f32_16x16x32_bf16 v[128:131], v[194:197], v[214:217], v[128:131]
	v_mfma_f32_16x16x32_bf16 v[116:119], v[178:181], v[224:227], v[116:119]
	v_mfma_f32_16x16x32_bf16 v[112:115], v[194:197], v[224:227], v[112:115]
	v_mfma_f32_16x16x32_bf16 v[100:103], v[178:181], v[232:235], v[100:103]
	v_mfma_f32_16x16x32_bf16 v[96:99], v[194:197], v[232:235], v[96:99]
	v_mfma_f32_16x16x32_bf16 v[68:71], v[178:181], v[240:243], v[68:71]
	v_mfma_f32_16x16x32_bf16 v[64:67], v[194:197], v[240:243], v[64:67]
	s_setprio 0
	s_barrier
	s_add_i32 s83, s83, s8
	v_lshl_add_u64 v[182:183], s[44:45], 0, v[152:153]
	s_mov_b32 m0, s83
	ds_read_b128 v[210:213], v188 offset:16384
	ds_read_b128 v[214:217], v188 offset:17408
	ds_read_b128 v[218:221], v188 offset:18432
	ds_read_b128 v[224:227], v188 offset:19456
	ds_read_b128 v[228:231], v188 offset:20480
	ds_read_b128 v[232:235], v188 offset:21504
	ds_read_b128 v[236:239], v188 offset:22528
	ds_read_b128 v[240:243], v188 offset:23552
	global_load_lds_dwordx4 v[182:183], off
	s_add_i32 m0, s83, 0x2000
	s_add_u32 s84, s44, 0x40000
	v_lshl_add_u64 v[198:199], s[44:45], 0, v[144:145]
	s_addc_u32 s85, s45, 0
	s_add_i32 s83, s86, s8
	global_load_lds_dwordx4 v[198:199], off
	v_lshl_add_u64 v[244:245], s[84:85], 0, v[152:153]
	s_mov_b32 m0, s83
	v_lshl_add_u64 v[246:247], s[62:63], 0, v[146:147]
	global_load_lds_dwordx4 v[244:245], off
	v_lshl_add_u64 v[244:245], s[84:85], 0, v[144:145]
	s_add_i32 m0, s83, 0x2000
	s_nop 0
	global_load_lds_dwordx4 v[244:245], off
	v_lshl_add_u64 v[244:245], s[62:63], 0, v[148:149]
	s_mov_b32 m0, s59
	s_nop 0
	global_load_lds_dwordx4 v[244:245], off
	s_mov_b32 m0, s66
	s_nop 0
	global_load_lds_dwordx4 v[246:247], off
	s_waitcnt vmcnt(8)
	s_waitcnt lgkmcnt(0)
	s_barrier
	s_setprio 1
	s_waitcnt lgkmcnt(0)
	v_mfma_f32_16x16x32_bf16 v[60:63], v[72:75], v[210:213], 0
	v_mfma_f32_16x16x32_bf16 v[56:59], v[80:83], v[210:213], 0
	v_mfma_f32_16x16x32_bf16 v[44:47], v[72:75], v[218:221], 0
	v_mfma_f32_16x16x32_bf16 v[40:43], v[80:83], v[218:221], 0
	v_mfma_f32_16x16x32_bf16 v[28:31], v[72:75], v[228:231], 0
	v_mfma_f32_16x16x32_bf16 v[24:27], v[80:83], v[228:231], 0
	v_mfma_f32_16x16x32_bf16 v[12:15], v[72:75], v[236:239], 0
	v_mfma_f32_16x16x32_bf16 v[8:11], v[80:83], v[236:239], 0
	v_mfma_f32_16x16x32_bf16 v[60:63], v[76:79], v[214:217], v[60:63]
	v_mfma_f32_16x16x32_bf16 v[56:59], v[88:91], v[214:217], v[56:59]
	v_mfma_f32_16x16x32_bf16 v[44:47], v[76:79], v[224:227], v[44:47]
	v_mfma_f32_16x16x32_bf16 v[40:43], v[88:91], v[224:227], v[40:43]
	v_mfma_f32_16x16x32_bf16 v[28:31], v[76:79], v[232:235], v[28:31]
	v_mfma_f32_16x16x32_bf16 v[24:27], v[88:91], v[232:235], v[24:27]
	v_mfma_f32_16x16x32_bf16 v[12:15], v[76:79], v[240:243], v[12:15]
	v_mfma_f32_16x16x32_bf16 v[8:11], v[88:91], v[240:243], v[8:11]
	s_setprio 0
	s_setprio 1
	v_mfma_f32_16x16x32_bf16 v[52:55], v[174:177], v[210:213], 0
	v_mfma_f32_16x16x32_bf16 v[48:51], v[190:193], v[210:213], 0
	v_mfma_f32_16x16x32_bf16 v[36:39], v[174:177], v[218:221], 0
	v_mfma_f32_16x16x32_bf16 v[32:35], v[190:193], v[218:221], 0
	v_mfma_f32_16x16x32_bf16 v[20:23], v[174:177], v[228:231], 0
	v_mfma_f32_16x16x32_bf16 v[16:19], v[190:193], v[228:231], 0
	v_mfma_f32_16x16x32_bf16 v[4:7], v[174:177], v[236:239], 0
	v_mfma_f32_16x16x32_bf16 v[0:3], v[190:193], v[236:239], 0
	v_mfma_f32_16x16x32_bf16 v[52:55], v[178:181], v[214:217], v[52:55]
	v_mfma_f32_16x16x32_bf16 v[48:51], v[194:197], v[214:217], v[48:51]
	v_mfma_f32_16x16x32_bf16 v[36:39], v[178:181], v[224:227], v[36:39]
	v_mfma_f32_16x16x32_bf16 v[32:35], v[194:197], v[224:227], v[32:35]
	v_mfma_f32_16x16x32_bf16 v[20:23], v[178:181], v[232:235], v[20:23]
	v_mfma_f32_16x16x32_bf16 v[16:19], v[194:197], v[232:235], v[16:19]
	v_mfma_f32_16x16x32_bf16 v[4:7], v[178:181], v[240:243], v[4:7]
	v_mfma_f32_16x16x32_bf16 v[0:3], v[194:197], v[240:243], v[0:3]
	s_setprio 0
	s_barrier
	s_add_i32 s83, 0, 0x18000
	s_add_i32 s84, 0, 0x1c000
	v_add_u32_e32 v88, s83, v185
	v_add_u32_e32 v189, s84, v185
	ds_read_b128 v[72:75], v88
	ds_read_b128 v[76:79], v88 offset:1024
	ds_read_b128 v[80:83], v88 offset:2048
	ds_read_b128 v[88:91], v88 offset:3072
	ds_read_b128 v[174:177], v189
	ds_read_b128 v[178:181], v189 offset:1024
	ds_read_b128 v[190:193], v189 offset:2048
	ds_read_b128 v[194:197], v189 offset:3072
	s_add_u32 s62, s62, 0x40000
	s_addc_u32 s63, s63, 0
	s_mov_b32 m0, s67
	v_lshl_add_u64 v[248:249], s[62:63], 0, v[148:149]
	ds_read_b128 v[210:213], v188 offset:32768
	ds_read_b128 v[214:217], v188 offset:33792
	ds_read_b128 v[218:221], v188 offset:34816
	ds_read_b128 v[224:227], v188 offset:35840
	ds_read_b128 v[228:231], v188 offset:36864
	ds_read_b128 v[232:235], v188 offset:37888
	ds_read_b128 v[236:239], v188 offset:38912
	ds_read_b128 v[240:243], v188 offset:39936
	global_load_lds_dwordx4 v[248:249], off
	v_lshl_add_u64 v[248:249], s[62:63], 0, v[146:147]
	s_mov_b32 m0, s68
	s_nop 0
	global_load_lds_dwordx4 v[248:249], off
	s_waitcnt vmcnt(8)
	s_waitcnt lgkmcnt(0)
	s_barrier
	s_setprio 1
	s_waitcnt lgkmcnt(0)
	v_mfma_f32_16x16x32_bf16 v[140:143], v[72:75], v[210:213], v[140:143]
	v_mfma_f32_16x16x32_bf16 v[136:139], v[80:83], v[210:213], v[136:139]
	v_mfma_f32_16x16x32_bf16 v[124:127], v[72:75], v[218:221], v[124:127]
	v_mfma_f32_16x16x32_bf16 v[120:123], v[80:83], v[218:221], v[120:123]
	v_mfma_f32_16x16x32_bf16 v[108:111], v[72:75], v[228:231], v[108:111]
	v_mfma_f32_16x16x32_bf16 v[104:107], v[80:83], v[228:231], v[104:107]
	v_mfma_f32_16x16x32_bf16 v[92:95], v[72:75], v[236:239], v[92:95]
	v_mfma_f32_16x16x32_bf16 v[84:87], v[80:83], v[236:239], v[84:87]
	v_mfma_f32_16x16x32_bf16 v[140:143], v[76:79], v[214:217], v[140:143]
	v_mfma_f32_16x16x32_bf16 v[136:139], v[88:91], v[214:217], v[136:139]
	v_mfma_f32_16x16x32_bf16 v[124:127], v[76:79], v[224:227], v[124:127]
	v_mfma_f32_16x16x32_bf16 v[120:123], v[88:91], v[224:227], v[120:123]
	v_mfma_f32_16x16x32_bf16 v[108:111], v[76:79], v[232:235], v[108:111]
	v_mfma_f32_16x16x32_bf16 v[104:107], v[88:91], v[232:235], v[104:107]
	v_mfma_f32_16x16x32_bf16 v[92:95], v[76:79], v[240:243], v[92:95]
	v_mfma_f32_16x16x32_bf16 v[84:87], v[88:91], v[240:243], v[84:87]
	s_setprio 0
	s_setprio 1
	v_mfma_f32_16x16x32_bf16 v[132:135], v[174:177], v[210:213], v[132:135]
	v_mfma_f32_16x16x32_bf16 v[128:131], v[190:193], v[210:213], v[128:131]
	v_mfma_f32_16x16x32_bf16 v[116:119], v[174:177], v[218:221], v[116:119]
	v_mfma_f32_16x16x32_bf16 v[112:115], v[190:193], v[218:221], v[112:115]
	v_mfma_f32_16x16x32_bf16 v[100:103], v[174:177], v[228:231], v[100:103]
	v_mfma_f32_16x16x32_bf16 v[96:99], v[190:193], v[228:231], v[96:99]
	v_mfma_f32_16x16x32_bf16 v[68:71], v[174:177], v[236:239], v[68:71]
	v_mfma_f32_16x16x32_bf16 v[64:67], v[190:193], v[236:239], v[64:67]
	v_mfma_f32_16x16x32_bf16 v[132:135], v[178:181], v[214:217], v[132:135]
	v_mfma_f32_16x16x32_bf16 v[128:131], v[194:197], v[214:217], v[128:131]
	v_mfma_f32_16x16x32_bf16 v[116:119], v[178:181], v[224:227], v[116:119]
	v_mfma_f32_16x16x32_bf16 v[112:115], v[194:197], v[224:227], v[112:115]
	v_mfma_f32_16x16x32_bf16 v[100:103], v[178:181], v[232:235], v[100:103]
	v_mfma_f32_16x16x32_bf16 v[96:99], v[194:197], v[232:235], v[96:99]
	v_mfma_f32_16x16x32_bf16 v[68:71], v[178:181], v[240:243], v[68:71]
	v_mfma_f32_16x16x32_bf16 v[64:67], v[194:197], v[240:243], v[64:67]
	s_setprio 0
	s_barrier
	s_add_i32 s62, s83, s8
	v_lshl_add_u64 v[182:183], v[182:183], 0, s[22:23]
	s_mov_b32 m0, s62
	ds_read_b128 v[210:213], v188 offset:49152
	ds_read_b128 v[214:217], v188 offset:50176
	ds_read_b128 v[218:221], v188 offset:51200
	ds_read_b128 v[224:227], v188 offset:52224
	ds_read_b128 v[228:231], v188 offset:53248
	ds_read_b128 v[232:235], v188 offset:54272
	ds_read_b128 v[236:239], v188 offset:55296
	ds_read_b128 v[240:243], v188 offset:56320
	global_load_lds_dwordx4 v[182:183], off
	s_add_i32 m0, s62, 0x2000
	s_add_u32 s44, s44, 0x40080
	v_lshl_add_u64 v[182:183], v[198:199], 0, s[22:23]
	s_addc_u32 s45, s45, 0
	s_add_i32 s62, s84, s8
	global_load_lds_dwordx4 v[182:183], off
	v_lshl_add_u64 v[182:183], s[44:45], 0, v[152:153]
	s_mov_b32 m0, s62
	s_nop 0
	global_load_lds_dwordx4 v[182:183], off
	v_lshl_add_u64 v[182:183], s[44:45], 0, v[144:145]
	s_add_i32 m0, s62, 0x2000
	s_nop 0
	global_load_lds_dwordx4 v[182:183], off
	v_lshl_add_u64 v[182:183], v[244:245], 0, s[22:23]
	s_mov_b32 m0, s69
	s_nop 0
	global_load_lds_dwordx4 v[182:183], off
	v_lshl_add_u64 v[182:183], v[246:247], 0, s[22:23]
	s_mov_b32 m0, s74
	s_nop 0
	global_load_lds_dwordx4 v[182:183], off
	s_waitcnt vmcnt(8)
	s_waitcnt lgkmcnt(0)
	s_barrier
	s_setprio 1
	s_waitcnt lgkmcnt(0)
	v_mfma_f32_16x16x32_bf16 v[60:63], v[72:75], v[210:213], v[60:63]
	v_mfma_f32_16x16x32_bf16 v[56:59], v[80:83], v[210:213], v[56:59]
	v_mfma_f32_16x16x32_bf16 v[44:47], v[72:75], v[218:221], v[44:47]
	v_mfma_f32_16x16x32_bf16 v[40:43], v[80:83], v[218:221], v[40:43]
	v_mfma_f32_16x16x32_bf16 v[28:31], v[72:75], v[228:231], v[28:31]
	v_mfma_f32_16x16x32_bf16 v[24:27], v[80:83], v[228:231], v[24:27]
	v_mfma_f32_16x16x32_bf16 v[12:15], v[72:75], v[236:239], v[12:15]
	v_mfma_f32_16x16x32_bf16 v[8:11], v[80:83], v[236:239], v[8:11]
	v_mfma_f32_16x16x32_bf16 v[60:63], v[76:79], v[214:217], v[60:63]
	v_mfma_f32_16x16x32_bf16 v[56:59], v[88:91], v[214:217], v[56:59]
	v_mfma_f32_16x16x32_bf16 v[44:47], v[76:79], v[224:227], v[44:47]
	v_mfma_f32_16x16x32_bf16 v[40:43], v[88:91], v[224:227], v[40:43]
	v_mfma_f32_16x16x32_bf16 v[28:31], v[76:79], v[232:235], v[28:31]
	v_mfma_f32_16x16x32_bf16 v[24:27], v[88:91], v[232:235], v[24:27]
	v_mfma_f32_16x16x32_bf16 v[12:15], v[76:79], v[240:243], v[12:15]
	v_mfma_f32_16x16x32_bf16 v[8:11], v[88:91], v[240:243], v[8:11]
	s_setprio 0
	s_setprio 1
	v_mfma_f32_16x16x32_bf16 v[52:55], v[174:177], v[210:213], v[52:55]
	v_mfma_f32_16x16x32_bf16 v[48:51], v[190:193], v[210:213], v[48:51]
	v_mfma_f32_16x16x32_bf16 v[36:39], v[174:177], v[218:221], v[36:39]
	v_mfma_f32_16x16x32_bf16 v[32:35], v[190:193], v[218:221], v[32:35]
	v_mfma_f32_16x16x32_bf16 v[20:23], v[174:177], v[228:231], v[20:23]
	v_mfma_f32_16x16x32_bf16 v[16:19], v[190:193], v[228:231], v[16:19]
	v_mfma_f32_16x16x32_bf16 v[4:7], v[174:177], v[236:239], v[4:7]
	v_mfma_f32_16x16x32_bf16 v[0:3], v[190:193], v[236:239], v[0:3]
	v_mfma_f32_16x16x32_bf16 v[52:55], v[178:181], v[214:217], v[52:55]
	v_mfma_f32_16x16x32_bf16 v[48:51], v[194:197], v[214:217], v[48:51]
	v_mfma_f32_16x16x32_bf16 v[36:39], v[178:181], v[224:227], v[36:39]
	v_mfma_f32_16x16x32_bf16 v[32:35], v[194:197], v[224:227], v[32:35]
	v_mfma_f32_16x16x32_bf16 v[20:23], v[178:181], v[232:235], v[20:23]
	v_mfma_f32_16x16x32_bf16 v[16:19], v[194:197], v[232:235], v[16:19]
	v_mfma_f32_16x16x32_bf16 v[4:7], v[178:181], v[240:243], v[4:7]
	v_mfma_f32_16x16x32_bf16 v[0:3], v[194:197], v[240:243], v[0:3]
	s_setprio 0
	s_barrier
	s_add_i32 s82, s82, 2
	s_add_u32 s80, s80, 0x100
	s_addc_u32 s81, s81, 0
	s_add_u32 s48, s48, 0x100
	s_addc_u32 s49, s49, 0
	s_cmp_gt_u32 s82, 13

.LBB0_704:
	s_ashr_i32 s21, s20, 31
	s_lshl_b64 s[48:49], s[20:21], 18
	v_readlane_b32 s19, v254, 14
	s_add_u32 s48, s19, s48
	v_readlane_b32 s19, v254, 15
	s_addc_u32 s49, s19, s49
	s_and_b64 s[50:51], s[46:47], exec
	s_cselect_b32 s21, s49, s45
	s_cselect_b32 s78, s48, s44
	s_ashr_i32 s19, s18, 31
	s_lshl_b64 s[50:51], s[18:19], 18
	v_readlane_b32 s19, v254, 10
	s_add_u32 s50, s19, s50
	v_readlane_b32 s19, v254, 11
	s_addc_u32 s51, s19, s51
	s_and_b64 s[62:63], s[46:47], exec
	s_cselect_b32 s19, s51, s61
	s_cselect_b32 s79, s50, s60
	s_add_u32 s80, s60, 0x100
	s_addc_u32 s81, s61, 0
	s_add_u32 s60, s44, 0x20080
	s_addc_u32 s61, s45, 0
	s_mov_b32 s82, -2
	s_add_u32 s44, s60, 0xfffe0080
	s_addc_u32 s45, s61, -1
	s_add_i32 s83, 0, 0x10000
	s_cmp_eq_u32 s82, 4
	s_cselect_b32 s63, s21, s45
	s_cselect_b32 s62, s78, s44
	s_cselect_b32 s45, s19, s81
	s_cselect_b32 s44, s79, s80
	s_add_i32 s86, 0, 0x14000
	v_add_u32_e32 v140, s83, v195
	v_add_u32_e32 v186, s86, v195
	ds_read_b128 v[124:127], v140
	ds_read_b128 v[132:135], v140 offset:1024
	ds_read_b128 v[136:139], v140 offset:2048
	ds_read_b128 v[140:143], v140 offset:3072
	ds_read_b128 v[144:147], v186
	ds_read_b128 v[148:151], v186 offset:1024
	ds_read_b128 v[182:185], v186 offset:2048
	ds_read_b128 v[186:189], v186 offset:3072
	v_lshl_add_u64 v[198:199], s[60:61], 0, v[180:181]
	s_add_i32 m0, s59, 0xc000
	ds_read_b128 v[190:193], v197
	ds_read_b128 v[210:213], v197 offset:1024
	ds_read_b128 v[214:217], v197 offset:2048
	ds_read_b128 v[218:221], v197 offset:3072
	ds_read_b128 v[224:227], v197 offset:4096
	ds_read_b128 v[228:231], v197 offset:5120
	ds_read_b128 v[232:235], v197 offset:6144
	ds_read_b128 v[236:239], v197 offset:7168
	global_load_lds_dwordx4 v[198:199], off
	v_lshl_add_u64 v[198:199], s[60:61], 0, v[178:179]
	s_add_i32 m0, s59, 0xe000
	s_nop 0
	global_load_lds_dwordx4 v[198:199], off
	s_waitcnt vmcnt(8)
	s_waitcnt lgkmcnt(0)
	s_barrier
	s_setprio 1
	s_waitcnt lgkmcnt(0)
	v_mfma_f32_16x16x32_bf16 v[128:131], v[124:127], v[190:193], 0
	v_mfma_f32_16x16x32_bf16 v[120:123], v[136:139], v[190:193], 0
	v_mfma_f32_16x16x32_bf16 v[108:111], v[124:127], v[214:217], 0
	v_mfma_f32_16x16x32_bf16 v[104:107], v[136:139], v[214:217], 0
	v_mfma_f32_16x16x32_bf16 v[92:95], v[124:127], v[224:227], 0
	v_mfma_f32_16x16x32_bf16 v[88:91], v[136:139], v[224:227], 0
	v_mfma_f32_16x16x32_bf16 v[76:79], v[124:127], v[232:235], 0
	v_mfma_f32_16x16x32_bf16 v[72:75], v[136:139], v[232:235], 0
	v_mfma_f32_16x16x32_bf16 v[128:131], v[132:135], v[210:213], v[128:131]
	v_mfma_f32_16x16x32_bf16 v[120:123], v[140:143], v[210:213], v[120:123]
	v_mfma_f32_16x16x32_bf16 v[108:111], v[132:135], v[218:221], v[108:111]
	v_mfma_f32_16x16x32_bf16 v[104:107], v[140:143], v[218:221], v[104:107]
	v_mfma_f32_16x16x32_bf16 v[92:95], v[132:135], v[228:231], v[92:95]
	v_mfma_f32_16x16x32_bf16 v[88:91], v[140:143], v[228:231], v[88:91]
	v_mfma_f32_16x16x32_bf16 v[76:79], v[132:135], v[236:239], v[76:79]
	v_mfma_f32_16x16x32_bf16 v[72:75], v[140:143], v[236:239], v[72:75]
	s_setprio 0
	s_setprio 1
	v_mfma_f32_16x16x32_bf16 v[116:119], v[144:147], v[190:193], 0
	v_mfma_f32_16x16x32_bf16 v[112:115], v[182:185], v[190:193], 0
	v_mfma_f32_16x16x32_bf16 v[100:103], v[144:147], v[214:217], 0
	v_mfma_f32_16x16x32_bf16 v[96:99], v[182:185], v[214:217], 0
	v_mfma_f32_16x16x32_bf16 v[84:87], v[144:147], v[224:227], 0
	v_mfma_f32_16x16x32_bf16 v[80:83], v[182:185], v[224:227], 0
	v_mfma_f32_16x16x32_bf16 v[68:71], v[144:147], v[232:235], 0
	v_mfma_f32_16x16x32_bf16 v[64:67], v[182:185], v[232:235], 0
	v_mfma_f32_16x16x32_bf16 v[116:119], v[148:151], v[210:213], v[116:119]
	v_mfma_f32_16x16x32_bf16 v[112:115], v[186:189], v[210:213], v[112:115]
	v_mfma_f32_16x16x32_bf16 v[100:103], v[148:151], v[218:221], v[100:103]
	v_mfma_f32_16x16x32_bf16 v[96:99], v[186:189], v[218:221], v[96:99]
	v_mfma_f32_16x16x32_bf16 v[84:87], v[148:151], v[228:231], v[84:87]
	v_mfma_f32_16x16x32_bf16 v[80:83], v[186:189], v[228:231], v[80:83]
	v_mfma_f32_16x16x32_bf16 v[68:71], v[148:151], v[236:239], v[68:71]
	v_mfma_f32_16x16x32_bf16 v[64:67], v[186:189], v[236:239], v[64:67]
	s_setprio 0
	s_barrier
	s_add_i32 s83, s83, s8
	v_lshl_add_u64 v[198:199], s[44:45], 0, v[152:153]
	s_mov_b32 m0, s83
	ds_read_b128 v[190:193], v197 offset:16384
	ds_read_b128 v[210:213], v197 offset:17408
	ds_read_b128 v[214:217], v197 offset:18432
	ds_read_b128 v[218:221], v197 offset:19456
	ds_read_b128 v[224:227], v197 offset:20480
	ds_read_b128 v[228:231], v197 offset:21504
	ds_read_b128 v[232:235], v197 offset:22528
	ds_read_b128 v[236:239], v197 offset:23552
	global_load_lds_dwordx4 v[198:199], off
	s_add_i32 m0, s83, 0x2000
	s_add_u32 s84, s44, 0x20000
	v_lshl_add_u64 v[240:241], s[44:45], 0, v[172:173]
	s_addc_u32 s85, s45, 0
	s_add_i32 s83, s86, s8
	global_load_lds_dwordx4 v[240:241], off
	v_lshl_add_u64 v[242:243], s[84:85], 0, v[152:153]
	s_mov_b32 m0, s83
	v_lshl_add_u64 v[244:245], s[62:63], 0, v[174:175]
	global_load_lds_dwordx4 v[242:243], off
	v_lshl_add_u64 v[242:243], s[84:85], 0, v[172:173]
	s_add_i32 m0, s83, 0x2000
	s_nop 0
	global_load_lds_dwordx4 v[242:243], off
	v_lshl_add_u64 v[242:243], s[62:63], 0, v[176:177]
	s_mov_b32 m0, s59
	s_nop 0
	global_load_lds_dwordx4 v[242:243], off
	s_mov_b32 m0, s66
	s_nop 0
	global_load_lds_dwordx4 v[244:245], off
	s_waitcnt vmcnt(8)
	s_waitcnt lgkmcnt(0)
	s_barrier
	s_setprio 1
	s_waitcnt lgkmcnt(0)
	v_mfma_f32_16x16x32_bf16 v[60:63], v[124:127], v[190:193], 0
	v_mfma_f32_16x16x32_bf16 v[56:59], v[136:139], v[190:193], 0
	v_mfma_f32_16x16x32_bf16 v[48:51], v[124:127], v[214:217], 0
	v_mfma_f32_16x16x32_bf16 v[40:43], v[136:139], v[214:217], 0
	v_mfma_f32_16x16x32_bf16 v[32:35], v[124:127], v[224:227], 0
	v_mfma_f32_16x16x32_bf16 v[24:27], v[136:139], v[224:227], 0
	v_mfma_f32_16x16x32_bf16 v[16:19], v[124:127], v[232:235], 0
	v_mfma_f32_16x16x32_bf16 v[8:11], v[136:139], v[232:235], 0
	v_mfma_f32_16x16x32_bf16 v[60:63], v[132:135], v[210:213], v[60:63]
	v_mfma_f32_16x16x32_bf16 v[56:59], v[140:143], v[210:213], v[56:59]
	v_mfma_f32_16x16x32_bf16 v[48:51], v[132:135], v[218:221], v[48:51]
	v_mfma_f32_16x16x32_bf16 v[40:43], v[140:143], v[218:221], v[40:43]
	v_mfma_f32_16x16x32_bf16 v[32:35], v[132:135], v[228:231], v[32:35]
	v_mfma_f32_16x16x32_bf16 v[24:27], v[140:143], v[228:231], v[24:27]
	v_mfma_f32_16x16x32_bf16 v[16:19], v[132:135], v[236:239], v[16:19]
	v_mfma_f32_16x16x32_bf16 v[8:11], v[140:143], v[236:239], v[8:11]
	s_setprio 0
	s_setprio 1
	v_mfma_f32_16x16x32_bf16 v[52:55], v[144:147], v[190:193], 0
	v_mfma_f32_16x16x32_bf16 v[44:47], v[182:185], v[190:193], 0
	v_mfma_f32_16x16x32_bf16 v[36:39], v[144:147], v[214:217], 0
	v_mfma_f32_16x16x32_bf16 v[28:31], v[182:185], v[214:217], 0
	v_mfma_f32_16x16x32_bf16 v[20:23], v[144:147], v[224:227], 0
	v_mfma_f32_16x16x32_bf16 v[12:15], v[182:185], v[224:227], 0
	v_mfma_f32_16x16x32_bf16 v[4:7], v[144:147], v[232:235], 0
	v_mfma_f32_16x16x32_bf16 v[0:3], v[182:185], v[232:235], 0
	v_mfma_f32_16x16x32_bf16 v[52:55], v[148:151], v[210:213], v[52:55]
	v_mfma_f32_16x16x32_bf16 v[44:47], v[186:189], v[210:213], v[44:47]
	v_mfma_f32_16x16x32_bf16 v[36:39], v[148:151], v[218:221], v[36:39]
	v_mfma_f32_16x16x32_bf16 v[28:31], v[186:189], v[218:221], v[28:31]
	v_mfma_f32_16x16x32_bf16 v[20:23], v[148:151], v[228:231], v[20:23]
	v_mfma_f32_16x16x32_bf16 v[12:15], v[186:189], v[228:231], v[12:15]
	v_mfma_f32_16x16x32_bf16 v[4:7], v[148:151], v[236:239], v[4:7]
	v_mfma_f32_16x16x32_bf16 v[0:3], v[186:189], v[236:239], v[0:3]
	s_setprio 0
	s_barrier
	s_add_i32 s83, 0, 0x18000
	s_add_i32 s84, 0, 0x1c000
	v_add_u32_e32 v140, s83, v195
	v_add_u32_e32 v186, s84, v195
	ds_read_b128 v[124:127], v140
	ds_read_b128 v[132:135], v140 offset:1024
	ds_read_b128 v[136:139], v140 offset:2048
	ds_read_b128 v[140:143], v140 offset:3072
	ds_read_b128 v[144:147], v186
	ds_read_b128 v[148:151], v186 offset:1024
	ds_read_b128 v[182:185], v186 offset:2048
	ds_read_b128 v[186:189], v186 offset:3072
	s_add_u32 s62, s62, 0x20000
	s_addc_u32 s63, s63, 0
	s_mov_b32 m0, s67
	v_lshl_add_u64 v[246:247], s[62:63], 0, v[176:177]
	ds_read_b128 v[190:193], v197 offset:32768
	ds_read_b128 v[210:213], v197 offset:33792
	ds_read_b128 v[214:217], v197 offset:34816
	ds_read_b128 v[218:221], v197 offset:35840
	ds_read_b128 v[224:227], v197 offset:36864
	ds_read_b128 v[228:231], v197 offset:37888
	ds_read_b128 v[232:235], v197 offset:38912
	ds_read_b128 v[236:239], v197 offset:39936
	global_load_lds_dwordx4 v[246:247], off
	v_lshl_add_u64 v[246:247], s[62:63], 0, v[174:175]
	s_mov_b32 m0, s68
	s_nop 0
	global_load_lds_dwordx4 v[246:247], off
	s_waitcnt vmcnt(8)
	s_waitcnt lgkmcnt(0)
	s_barrier
	s_setprio 1
	s_waitcnt lgkmcnt(0)
	v_mfma_f32_16x16x32_bf16 v[128:131], v[124:127], v[190:193], v[128:131]
	v_mfma_f32_16x16x32_bf16 v[120:123], v[136:139], v[190:193], v[120:123]
	v_mfma_f32_16x16x32_bf16 v[108:111], v[124:127], v[214:217], v[108:111]
	v_mfma_f32_16x16x32_bf16 v[104:107], v[136:139], v[214:217], v[104:107]
	v_mfma_f32_16x16x32_bf16 v[92:95], v[124:127], v[224:227], v[92:95]
	v_mfma_f32_16x16x32_bf16 v[88:91], v[136:139], v[224:227], v[88:91]
	v_mfma_f32_16x16x32_bf16 v[76:79], v[124:127], v[232:235], v[76:79]
	v_mfma_f32_16x16x32_bf16 v[72:75], v[136:139], v[232:235], v[72:75]
	v_mfma_f32_16x16x32_bf16 v[128:131], v[132:135], v[210:213], v[128:131]
	v_mfma_f32_16x16x32_bf16 v[120:123], v[140:143], v[210:213], v[120:123]
	v_mfma_f32_16x16x32_bf16 v[108:111], v[132:135], v[218:221], v[108:111]
	v_mfma_f32_16x16x32_bf16 v[104:107], v[140:143], v[218:221], v[104:107]
	v_mfma_f32_16x16x32_bf16 v[92:95], v[132:135], v[228:231], v[92:95]
	v_mfma_f32_16x16x32_bf16 v[88:91], v[140:143], v[228:231], v[88:91]
	v_mfma_f32_16x16x32_bf16 v[76:79], v[132:135], v[236:239], v[76:79]
	v_mfma_f32_16x16x32_bf16 v[72:75], v[140:143], v[236:239], v[72:75]
	s_setprio 0
	s_setprio 1
	v_mfma_f32_16x16x32_bf16 v[116:119], v[144:147], v[190:193], v[116:119]
	v_mfma_f32_16x16x32_bf16 v[112:115], v[182:185], v[190:193], v[112:115]
	v_mfma_f32_16x16x32_bf16 v[100:103], v[144:147], v[214:217], v[100:103]
	v_mfma_f32_16x16x32_bf16 v[96:99], v[182:185], v[214:217], v[96:99]
	v_mfma_f32_16x16x32_bf16 v[84:87], v[144:147], v[224:227], v[84:87]
	v_mfma_f32_16x16x32_bf16 v[80:83], v[182:185], v[224:227], v[80:83]
	v_mfma_f32_16x16x32_bf16 v[68:71], v[144:147], v[232:235], v[68:71]
	v_mfma_f32_16x16x32_bf16 v[64:67], v[182:185], v[232:235], v[64:67]
	v_mfma_f32_16x16x32_bf16 v[116:119], v[148:151], v[210:213], v[116:119]
	v_mfma_f32_16x16x32_bf16 v[112:115], v[186:189], v[210:213], v[112:115]
	v_mfma_f32_16x16x32_bf16 v[100:103], v[148:151], v[218:221], v[100:103]
	v_mfma_f32_16x16x32_bf16 v[96:99], v[186:189], v[218:221], v[96:99]
	v_mfma_f32_16x16x32_bf16 v[84:87], v[148:151], v[228:231], v[84:87]
	v_mfma_f32_16x16x32_bf16 v[80:83], v[186:189], v[228:231], v[80:83]
	v_mfma_f32_16x16x32_bf16 v[68:71], v[148:151], v[236:239], v[68:71]
	v_mfma_f32_16x16x32_bf16 v[64:67], v[186:189], v[236:239], v[64:67]
	s_setprio 0
	s_barrier
	s_add_i32 s62, s83, s8
	v_lshl_add_u64 v[198:199], v[198:199], 0, s[22:23]
	s_mov_b32 m0, s62
	ds_read_b128 v[190:193], v197 offset:49152
	ds_read_b128 v[210:213], v197 offset:50176
	ds_read_b128 v[214:217], v197 offset:51200
	ds_read_b128 v[218:221], v197 offset:52224
	ds_read_b128 v[224:227], v197 offset:53248
	ds_read_b128 v[228:231], v197 offset:54272
	ds_read_b128 v[232:235], v197 offset:55296
	ds_read_b128 v[236:239], v197 offset:56320
	global_load_lds_dwordx4 v[198:199], off
	s_add_i32 m0, s62, 0x2000
	s_add_u32 s44, s44, 0x20080
	v_lshl_add_u64 v[198:199], v[240:241], 0, s[22:23]
	s_addc_u32 s45, s45, 0
	s_add_i32 s62, s84, s8
	global_load_lds_dwordx4 v[198:199], off
	v_lshl_add_u64 v[198:199], s[44:45], 0, v[152:153]
	s_mov_b32 m0, s62
	s_nop 0
	global_load_lds_dwordx4 v[198:199], off
	v_lshl_add_u64 v[198:199], s[44:45], 0, v[172:173]
	s_add_i32 m0, s62, 0x2000
	s_nop 0
	global_load_lds_dwordx4 v[198:199], off
	v_lshl_add_u64 v[198:199], v[242:243], 0, s[22:23]
	s_mov_b32 m0, s69
	s_nop 0
	global_load_lds_dwordx4 v[198:199], off
	v_lshl_add_u64 v[198:199], v[244:245], 0, s[22:23]
	s_mov_b32 m0, s74
	s_nop 0
	global_load_lds_dwordx4 v[198:199], off
	s_waitcnt vmcnt(8)
	s_waitcnt lgkmcnt(0)
	s_barrier
	s_setprio 1
	s_waitcnt lgkmcnt(0)
	v_mfma_f32_16x16x32_bf16 v[60:63], v[124:127], v[190:193], v[60:63]
	v_mfma_f32_16x16x32_bf16 v[56:59], v[136:139], v[190:193], v[56:59]
	v_mfma_f32_16x16x32_bf16 v[48:51], v[124:127], v[214:217], v[48:51]
	v_mfma_f32_16x16x32_bf16 v[40:43], v[136:139], v[214:217], v[40:43]
	v_mfma_f32_16x16x32_bf16 v[32:35], v[124:127], v[224:227], v[32:35]
	v_mfma_f32_16x16x32_bf16 v[24:27], v[136:139], v[224:227], v[24:27]
	v_mfma_f32_16x16x32_bf16 v[16:19], v[124:127], v[232:235], v[16:19]
	v_mfma_f32_16x16x32_bf16 v[8:11], v[136:139], v[232:235], v[8:11]
	v_mfma_f32_16x16x32_bf16 v[60:63], v[132:135], v[210:213], v[60:63]
	v_mfma_f32_16x16x32_bf16 v[56:59], v[140:143], v[210:213], v[56:59]
	v_mfma_f32_16x16x32_bf16 v[48:51], v[132:135], v[218:221], v[48:51]
	v_mfma_f32_16x16x32_bf16 v[40:43], v[140:143], v[218:221], v[40:43]
	v_mfma_f32_16x16x32_bf16 v[32:35], v[132:135], v[228:231], v[32:35]
	v_mfma_f32_16x16x32_bf16 v[24:27], v[140:143], v[228:231], v[24:27]
	v_mfma_f32_16x16x32_bf16 v[16:19], v[132:135], v[236:239], v[16:19]
	v_mfma_f32_16x16x32_bf16 v[8:11], v[140:143], v[236:239], v[8:11]
	s_setprio 0
	s_setprio 1
	v_mfma_f32_16x16x32_bf16 v[52:55], v[144:147], v[190:193], v[52:55]
	v_mfma_f32_16x16x32_bf16 v[44:47], v[182:185], v[190:193], v[44:47]
	v_mfma_f32_16x16x32_bf16 v[36:39], v[144:147], v[214:217], v[36:39]
	v_mfma_f32_16x16x32_bf16 v[28:31], v[182:185], v[214:217], v[28:31]
	v_mfma_f32_16x16x32_bf16 v[20:23], v[144:147], v[224:227], v[20:23]
	v_mfma_f32_16x16x32_bf16 v[12:15], v[182:185], v[224:227], v[12:15]
	v_mfma_f32_16x16x32_bf16 v[4:7], v[144:147], v[232:235], v[4:7]
	v_mfma_f32_16x16x32_bf16 v[0:3], v[182:185], v[232:235], v[0:3]
	v_mfma_f32_16x16x32_bf16 v[52:55], v[148:151], v[210:213], v[52:55]
	v_mfma_f32_16x16x32_bf16 v[44:47], v[186:189], v[210:213], v[44:47]
	v_mfma_f32_16x16x32_bf16 v[36:39], v[148:151], v[218:221], v[36:39]
	v_mfma_f32_16x16x32_bf16 v[28:31], v[186:189], v[218:221], v[28:31]
	v_mfma_f32_16x16x32_bf16 v[20:23], v[148:151], v[228:231], v[20:23]
	v_mfma_f32_16x16x32_bf16 v[12:15], v[186:189], v[228:231], v[12:15]
	v_mfma_f32_16x16x32_bf16 v[4:7], v[148:151], v[236:239], v[4:7]
	v_mfma_f32_16x16x32_bf16 v[0:3], v[186:189], v[236:239], v[0:3]
	s_setprio 0
	s_barrier
	s_add_i32 s82, s82, 2
	s_add_u32 s80, s80, 0x100
	s_addc_u32 s81, s81, 0
	s_add_u32 s60, s60, 0x100
	s_addc_u32 s61, s61, 0
	s_cmp_gt_u32 s82, 5

.LBB0_724:
	s_ashr_i32 s21, s20, 31
	s_lshl_b64 s[48:49], s[20:21], 18
	v_readlane_b32 s19, v254, 28
	s_add_u32 s48, s19, s48
	v_readlane_b32 s19, v254, 29
	s_addc_u32 s49, s19, s49
	s_and_b64 s[50:51], s[46:47], exec
	s_cselect_b32 s21, s49, s45
	s_cselect_b32 s78, s48, s44
	s_ashr_i32 s19, s18, 31
	s_lshl_b64 s[50:51], s[18:19], 18
	v_readlane_b32 s19, v254, 24
	s_add_u32 s50, s19, s50
	v_readlane_b32 s19, v254, 25
	s_addc_u32 s51, s19, s51
	s_and_b64 s[62:63], s[46:47], exec
	s_cselect_b32 s19, s51, s61
	s_cselect_b32 s79, s50, s60
	s_add_u32 s80, s60, 0x100
	s_addc_u32 s81, s61, 0
	s_add_u32 s60, s44, 0x20080
	s_addc_u32 s61, s45, 0
	s_mov_b32 s82, -2
	s_add_u32 s44, s60, 0xfffe0080
	s_addc_u32 s45, s61, -1
	s_add_i32 s83, 0, 0x10000
	s_cmp_eq_u32 s82, 4
	s_cselect_b32 s63, s21, s45
	s_cselect_b32 s62, s78, s44
	s_cselect_b32 s45, s19, s81
	s_cselect_b32 s44, s79, s80
	s_add_i32 s86, 0, 0x14000
	v_add_u32_e32 v140, s83, v181
	v_add_u32_e32 v178, s86, v181
	ds_read_b128 v[128:131], v140
	ds_read_b128 v[132:135], v140 offset:1024
	ds_read_b128 v[136:139], v140 offset:2048
	ds_read_b128 v[140:143], v140 offset:3072
	ds_read_b128 v[174:177], v178
	ds_read_b128 v[184:187], v178 offset:1024
	ds_read_b128 v[188:191], v178 offset:2048
	ds_read_b128 v[192:195], v178 offset:3072
	v_lshl_add_u64 v[178:179], s[60:61], 0, v[172:173]
	s_add_i32 m0, s59, 0xc000
	ds_read_b128 v[196:199], v183
	ds_read_b128 v[210:213], v183 offset:1024
	ds_read_b128 v[214:217], v183 offset:2048
	ds_read_b128 v[218:221], v183 offset:3072
	ds_read_b128 v[224:227], v183 offset:4096
	ds_read_b128 v[228:231], v183 offset:5120
	ds_read_b128 v[232:235], v183 offset:6144
	ds_read_b128 v[236:239], v183 offset:7168
	global_load_lds_dwordx4 v[178:179], off
	v_lshl_add_u64 v[178:179], s[60:61], 0, v[150:151]
	s_add_i32 m0, s59, 0xe000
	s_nop 0
	global_load_lds_dwordx4 v[178:179], off
	s_waitcnt vmcnt(8)
	s_waitcnt lgkmcnt(0)
	s_barrier
	s_setprio 1
	s_waitcnt lgkmcnt(0)
	v_mfma_f32_16x16x32_bf16 v[124:127], v[128:131], v[196:199], 0
	v_mfma_f32_16x16x32_bf16 v[120:123], v[136:139], v[196:199], 0
	v_mfma_f32_16x16x32_bf16 v[108:111], v[128:131], v[214:217], 0
	v_mfma_f32_16x16x32_bf16 v[104:107], v[136:139], v[214:217], 0
	v_mfma_f32_16x16x32_bf16 v[92:95], v[128:131], v[224:227], 0
	v_mfma_f32_16x16x32_bf16 v[88:91], v[136:139], v[224:227], 0
	v_mfma_f32_16x16x32_bf16 v[76:79], v[128:131], v[232:235], 0
	v_mfma_f32_16x16x32_bf16 v[72:75], v[136:139], v[232:235], 0
	v_mfma_f32_16x16x32_bf16 v[124:127], v[132:135], v[210:213], v[124:127]
	v_mfma_f32_16x16x32_bf16 v[120:123], v[140:143], v[210:213], v[120:123]
	v_mfma_f32_16x16x32_bf16 v[108:111], v[132:135], v[218:221], v[108:111]
	v_mfma_f32_16x16x32_bf16 v[104:107], v[140:143], v[218:221], v[104:107]
	v_mfma_f32_16x16x32_bf16 v[92:95], v[132:135], v[228:231], v[92:95]
	v_mfma_f32_16x16x32_bf16 v[88:91], v[140:143], v[228:231], v[88:91]
	v_mfma_f32_16x16x32_bf16 v[76:79], v[132:135], v[236:239], v[76:79]
	v_mfma_f32_16x16x32_bf16 v[72:75], v[140:143], v[236:239], v[72:75]
	s_setprio 0
	s_setprio 1
	v_mfma_f32_16x16x32_bf16 v[116:119], v[174:177], v[196:199], 0
	v_mfma_f32_16x16x32_bf16 v[112:115], v[188:191], v[196:199], 0
	v_mfma_f32_16x16x32_bf16 v[100:103], v[174:177], v[214:217], 0
	v_mfma_f32_16x16x32_bf16 v[96:99], v[188:191], v[214:217], 0
	v_mfma_f32_16x16x32_bf16 v[84:87], v[174:177], v[224:227], 0
	v_mfma_f32_16x16x32_bf16 v[80:83], v[188:191], v[224:227], 0
	v_mfma_f32_16x16x32_bf16 v[68:71], v[174:177], v[232:235], 0
	v_mfma_f32_16x16x32_bf16 v[64:67], v[188:191], v[232:235], 0
	v_mfma_f32_16x16x32_bf16 v[116:119], v[184:187], v[210:213], v[116:119]
	v_mfma_f32_16x16x32_bf16 v[112:115], v[192:195], v[210:213], v[112:115]
	v_mfma_f32_16x16x32_bf16 v[100:103], v[184:187], v[218:221], v[100:103]
	v_mfma_f32_16x16x32_bf16 v[96:99], v[192:195], v[218:221], v[96:99]
	v_mfma_f32_16x16x32_bf16 v[84:87], v[184:187], v[228:231], v[84:87]
	v_mfma_f32_16x16x32_bf16 v[80:83], v[192:195], v[228:231], v[80:83]
	v_mfma_f32_16x16x32_bf16 v[68:71], v[184:187], v[236:239], v[68:71]
	v_mfma_f32_16x16x32_bf16 v[64:67], v[192:195], v[236:239], v[64:67]
	s_setprio 0
	s_barrier
	s_add_i32 s83, s83, s8
	v_lshl_add_u64 v[178:179], s[44:45], 0, v[152:153]
	s_mov_b32 m0, s83
	ds_read_b128 v[196:199], v183 offset:16384
	ds_read_b128 v[210:213], v183 offset:17408
	ds_read_b128 v[214:217], v183 offset:18432
	ds_read_b128 v[218:221], v183 offset:19456
	ds_read_b128 v[224:227], v183 offset:20480
	ds_read_b128 v[228:231], v183 offset:21504
	ds_read_b128 v[232:235], v183 offset:22528
	ds_read_b128 v[236:239], v183 offset:23552
	global_load_lds_dwordx4 v[178:179], off
	s_add_i32 m0, s83, 0x2000
	s_add_u32 s84, s44, 0x20000
	v_lshl_add_u64 v[240:241], s[44:45], 0, v[144:145]
	s_addc_u32 s85, s45, 0
	s_add_i32 s83, s86, s8
	global_load_lds_dwordx4 v[240:241], off
	v_lshl_add_u64 v[242:243], s[84:85], 0, v[152:153]
	s_mov_b32 m0, s83
	v_lshl_add_u64 v[244:245], s[62:63], 0, v[146:147]
	global_load_lds_dwordx4 v[242:243], off
	v_lshl_add_u64 v[242:243], s[84:85], 0, v[144:145]
	s_add_i32 m0, s83, 0x2000
	s_nop 0
	global_load_lds_dwordx4 v[242:243], off
	v_lshl_add_u64 v[242:243], s[62:63], 0, v[148:149]
	s_mov_b32 m0, s59
	s_nop 0
	global_load_lds_dwordx4 v[242:243], off
	s_mov_b32 m0, s66
	s_nop 0
	global_load_lds_dwordx4 v[244:245], off
	s_waitcnt vmcnt(8)
	s_waitcnt lgkmcnt(0)
	s_barrier
	s_setprio 1
	s_waitcnt lgkmcnt(0)
	v_mfma_f32_16x16x32_bf16 v[60:63], v[128:131], v[196:199], 0
	v_mfma_f32_16x16x32_bf16 v[56:59], v[136:139], v[196:199], 0
	v_mfma_f32_16x16x32_bf16 v[44:47], v[128:131], v[214:217], 0
	v_mfma_f32_16x16x32_bf16 v[40:43], v[136:139], v[214:217], 0
	v_mfma_f32_16x16x32_bf16 v[28:31], v[128:131], v[224:227], 0
	v_mfma_f32_16x16x32_bf16 v[24:27], v[136:139], v[224:227], 0
	v_mfma_f32_16x16x32_bf16 v[12:15], v[128:131], v[232:235], 0
	v_mfma_f32_16x16x32_bf16 v[8:11], v[136:139], v[232:235], 0
	v_mfma_f32_16x16x32_bf16 v[60:63], v[132:135], v[210:213], v[60:63]
	v_mfma_f32_16x16x32_bf16 v[56:59], v[140:143], v[210:213], v[56:59]
	v_mfma_f32_16x16x32_bf16 v[44:47], v[132:135], v[218:221], v[44:47]
	v_mfma_f32_16x16x32_bf16 v[40:43], v[140:143], v[218:221], v[40:43]
	v_mfma_f32_16x16x32_bf16 v[28:31], v[132:135], v[228:231], v[28:31]
	v_mfma_f32_16x16x32_bf16 v[24:27], v[140:143], v[228:231], v[24:27]
	v_mfma_f32_16x16x32_bf16 v[12:15], v[132:135], v[236:239], v[12:15]
	v_mfma_f32_16x16x32_bf16 v[8:11], v[140:143], v[236:239], v[8:11]
	s_setprio 0
	s_setprio 1
	v_mfma_f32_16x16x32_bf16 v[52:55], v[174:177], v[196:199], 0
	v_mfma_f32_16x16x32_bf16 v[48:51], v[188:191], v[196:199], 0
	v_mfma_f32_16x16x32_bf16 v[36:39], v[174:177], v[214:217], 0
	v_mfma_f32_16x16x32_bf16 v[32:35], v[188:191], v[214:217], 0
	v_mfma_f32_16x16x32_bf16 v[20:23], v[174:177], v[224:227], 0
	v_mfma_f32_16x16x32_bf16 v[16:19], v[188:191], v[224:227], 0
	v_mfma_f32_16x16x32_bf16 v[4:7], v[174:177], v[232:235], 0
	v_mfma_f32_16x16x32_bf16 v[0:3], v[188:191], v[232:235], 0
	v_mfma_f32_16x16x32_bf16 v[52:55], v[184:187], v[210:213], v[52:55]
	v_mfma_f32_16x16x32_bf16 v[48:51], v[192:195], v[210:213], v[48:51]
	v_mfma_f32_16x16x32_bf16 v[36:39], v[184:187], v[218:221], v[36:39]
	v_mfma_f32_16x16x32_bf16 v[32:35], v[192:195], v[218:221], v[32:35]
	v_mfma_f32_16x16x32_bf16 v[20:23], v[184:187], v[228:231], v[20:23]
	v_mfma_f32_16x16x32_bf16 v[16:19], v[192:195], v[228:231], v[16:19]
	v_mfma_f32_16x16x32_bf16 v[4:7], v[184:187], v[236:239], v[4:7]
	v_mfma_f32_16x16x32_bf16 v[0:3], v[192:195], v[236:239], v[0:3]
	s_setprio 0
	s_barrier
	s_add_i32 s83, 0, 0x18000
	s_add_i32 s84, 0, 0x1c000
	v_add_u32_e32 v140, s83, v181
	v_add_u32_e32 v192, s84, v181
	ds_read_b128 v[128:131], v140
	ds_read_b128 v[132:135], v140 offset:1024
	ds_read_b128 v[136:139], v140 offset:2048
	ds_read_b128 v[140:143], v140 offset:3072
	ds_read_b128 v[174:177], v192
	ds_read_b128 v[184:187], v192 offset:1024
	ds_read_b128 v[188:191], v192 offset:2048
	ds_read_b128 v[192:195], v192 offset:3072
	s_add_u32 s62, s62, 0x20000
	s_addc_u32 s63, s63, 0
	s_mov_b32 m0, s67
	v_lshl_add_u64 v[246:247], s[62:63], 0, v[148:149]
	ds_read_b128 v[196:199], v183 offset:32768
	ds_read_b128 v[210:213], v183 offset:33792
	ds_read_b128 v[214:217], v183 offset:34816
	ds_read_b128 v[218:221], v183 offset:35840
	ds_read_b128 v[224:227], v183 offset:36864
	ds_read_b128 v[228:231], v183 offset:37888
	ds_read_b128 v[232:235], v183 offset:38912
	ds_read_b128 v[236:239], v183 offset:39936
	global_load_lds_dwordx4 v[246:247], off
	v_lshl_add_u64 v[246:247], s[62:63], 0, v[146:147]
	s_mov_b32 m0, s68
	s_nop 0
	global_load_lds_dwordx4 v[246:247], off
	s_waitcnt vmcnt(8)
	s_waitcnt lgkmcnt(0)
	s_barrier
	s_setprio 1
	s_waitcnt lgkmcnt(0)
	v_mfma_f32_16x16x32_bf16 v[124:127], v[128:131], v[196:199], v[124:127]
	v_mfma_f32_16x16x32_bf16 v[120:123], v[136:139], v[196:199], v[120:123]
	v_mfma_f32_16x16x32_bf16 v[108:111], v[128:131], v[214:217], v[108:111]
	v_mfma_f32_16x16x32_bf16 v[104:107], v[136:139], v[214:217], v[104:107]
	v_mfma_f32_16x16x32_bf16 v[92:95], v[128:131], v[224:227], v[92:95]
	v_mfma_f32_16x16x32_bf16 v[88:91], v[136:139], v[224:227], v[88:91]
	v_mfma_f32_16x16x32_bf16 v[76:79], v[128:131], v[232:235], v[76:79]
	v_mfma_f32_16x16x32_bf16 v[72:75], v[136:139], v[232:235], v[72:75]
	v_mfma_f32_16x16x32_bf16 v[124:127], v[132:135], v[210:213], v[124:127]
	v_mfma_f32_16x16x32_bf16 v[120:123], v[140:143], v[210:213], v[120:123]
	v_mfma_f32_16x16x32_bf16 v[108:111], v[132:135], v[218:221], v[108:111]
	v_mfma_f32_16x16x32_bf16 v[104:107], v[140:143], v[218:221], v[104:107]
	v_mfma_f32_16x16x32_bf16 v[92:95], v[132:135], v[228:231], v[92:95]
	v_mfma_f32_16x16x32_bf16 v[88:91], v[140:143], v[228:231], v[88:91]
	v_mfma_f32_16x16x32_bf16 v[76:79], v[132:135], v[236:239], v[76:79]
	v_mfma_f32_16x16x32_bf16 v[72:75], v[140:143], v[236:239], v[72:75]
	s_setprio 0
	s_setprio 1
	v_mfma_f32_16x16x32_bf16 v[116:119], v[174:177], v[196:199], v[116:119]
	v_mfma_f32_16x16x32_bf16 v[112:115], v[188:191], v[196:199], v[112:115]
	v_mfma_f32_16x16x32_bf16 v[100:103], v[174:177], v[214:217], v[100:103]
	v_mfma_f32_16x16x32_bf16 v[96:99], v[188:191], v[214:217], v[96:99]
	v_mfma_f32_16x16x32_bf16 v[84:87], v[174:177], v[224:227], v[84:87]
	v_mfma_f32_16x16x32_bf16 v[80:83], v[188:191], v[224:227], v[80:83]
	v_mfma_f32_16x16x32_bf16 v[68:71], v[174:177], v[232:235], v[68:71]
	v_mfma_f32_16x16x32_bf16 v[64:67], v[188:191], v[232:235], v[64:67]
	v_mfma_f32_16x16x32_bf16 v[116:119], v[184:187], v[210:213], v[116:119]
	v_mfma_f32_16x16x32_bf16 v[112:115], v[192:195], v[210:213], v[112:115]
	v_mfma_f32_16x16x32_bf16 v[100:103], v[184:187], v[218:221], v[100:103]
	v_mfma_f32_16x16x32_bf16 v[96:99], v[192:195], v[218:221], v[96:99]
	v_mfma_f32_16x16x32_bf16 v[84:87], v[184:187], v[228:231], v[84:87]
	v_mfma_f32_16x16x32_bf16 v[80:83], v[192:195], v[228:231], v[80:83]
	v_mfma_f32_16x16x32_bf16 v[68:71], v[184:187], v[236:239], v[68:71]
	v_mfma_f32_16x16x32_bf16 v[64:67], v[192:195], v[236:239], v[64:67]
	s_setprio 0
	s_barrier
	s_add_i32 s62, s83, s8
	v_lshl_add_u64 v[178:179], v[178:179], 0, s[22:23]
	s_mov_b32 m0, s62
	ds_read_b128 v[196:199], v183 offset:49152
	ds_read_b128 v[210:213], v183 offset:50176
	ds_read_b128 v[214:217], v183 offset:51200
	ds_read_b128 v[218:221], v183 offset:52224
	ds_read_b128 v[224:227], v183 offset:53248
	ds_read_b128 v[228:231], v183 offset:54272
	ds_read_b128 v[232:235], v183 offset:55296
	ds_read_b128 v[236:239], v183 offset:56320
	global_load_lds_dwordx4 v[178:179], off
	s_add_i32 m0, s62, 0x2000
	s_add_u32 s44, s44, 0x20080
	v_lshl_add_u64 v[178:179], v[240:241], 0, s[22:23]
	s_addc_u32 s45, s45, 0
	s_add_i32 s62, s84, s8
	global_load_lds_dwordx4 v[178:179], off
	v_lshl_add_u64 v[178:179], s[44:45], 0, v[152:153]
	s_mov_b32 m0, s62
	s_nop 0
	global_load_lds_dwordx4 v[178:179], off
	v_lshl_add_u64 v[178:179], s[44:45], 0, v[144:145]
	s_add_i32 m0, s62, 0x2000
	s_nop 0
	global_load_lds_dwordx4 v[178:179], off
	v_lshl_add_u64 v[178:179], v[242:243], 0, s[22:23]
	s_mov_b32 m0, s69
	s_nop 0
	global_load_lds_dwordx4 v[178:179], off
	v_lshl_add_u64 v[178:179], v[244:245], 0, s[22:23]
	s_mov_b32 m0, s74
	s_nop 0
	global_load_lds_dwordx4 v[178:179], off
	s_waitcnt vmcnt(8)
	s_waitcnt lgkmcnt(0)
	s_barrier
	s_setprio 1
	s_waitcnt lgkmcnt(0)
	v_mfma_f32_16x16x32_bf16 v[60:63], v[128:131], v[196:199], v[60:63]
	v_mfma_f32_16x16x32_bf16 v[56:59], v[136:139], v[196:199], v[56:59]
	v_mfma_f32_16x16x32_bf16 v[44:47], v[128:131], v[214:217], v[44:47]
	v_mfma_f32_16x16x32_bf16 v[40:43], v[136:139], v[214:217], v[40:43]
	v_mfma_f32_16x16x32_bf16 v[28:31], v[128:131], v[224:227], v[28:31]
	v_mfma_f32_16x16x32_bf16 v[24:27], v[136:139], v[224:227], v[24:27]
	v_mfma_f32_16x16x32_bf16 v[12:15], v[128:131], v[232:235], v[12:15]
	v_mfma_f32_16x16x32_bf16 v[8:11], v[136:139], v[232:235], v[8:11]
	v_mfma_f32_16x16x32_bf16 v[60:63], v[132:135], v[210:213], v[60:63]
	v_mfma_f32_16x16x32_bf16 v[56:59], v[140:143], v[210:213], v[56:59]
	v_mfma_f32_16x16x32_bf16 v[44:47], v[132:135], v[218:221], v[44:47]
	v_mfma_f32_16x16x32_bf16 v[40:43], v[140:143], v[218:221], v[40:43]
	v_mfma_f32_16x16x32_bf16 v[28:31], v[132:135], v[228:231], v[28:31]
	v_mfma_f32_16x16x32_bf16 v[24:27], v[140:143], v[228:231], v[24:27]
	v_mfma_f32_16x16x32_bf16 v[12:15], v[132:135], v[236:239], v[12:15]
	v_mfma_f32_16x16x32_bf16 v[8:11], v[140:143], v[236:239], v[8:11]
	s_setprio 0
	s_setprio 1
	v_mfma_f32_16x16x32_bf16 v[52:55], v[174:177], v[196:199], v[52:55]
	v_mfma_f32_16x16x32_bf16 v[48:51], v[188:191], v[196:199], v[48:51]
	v_mfma_f32_16x16x32_bf16 v[36:39], v[174:177], v[214:217], v[36:39]
	v_mfma_f32_16x16x32_bf16 v[32:35], v[188:191], v[214:217], v[32:35]
	v_mfma_f32_16x16x32_bf16 v[20:23], v[174:177], v[224:227], v[20:23]
	v_mfma_f32_16x16x32_bf16 v[16:19], v[188:191], v[224:227], v[16:19]
	v_mfma_f32_16x16x32_bf16 v[4:7], v[174:177], v[232:235], v[4:7]
	v_mfma_f32_16x16x32_bf16 v[0:3], v[188:191], v[232:235], v[0:3]
	v_mfma_f32_16x16x32_bf16 v[52:55], v[184:187], v[210:213], v[52:55]
	v_mfma_f32_16x16x32_bf16 v[48:51], v[192:195], v[210:213], v[48:51]
	v_mfma_f32_16x16x32_bf16 v[36:39], v[184:187], v[218:221], v[36:39]
	v_mfma_f32_16x16x32_bf16 v[32:35], v[192:195], v[218:221], v[32:35]
	v_mfma_f32_16x16x32_bf16 v[20:23], v[184:187], v[228:231], v[20:23]
	v_mfma_f32_16x16x32_bf16 v[16:19], v[192:195], v[228:231], v[16:19]
	v_mfma_f32_16x16x32_bf16 v[4:7], v[184:187], v[236:239], v[4:7]
	v_mfma_f32_16x16x32_bf16 v[0:3], v[192:195], v[236:239], v[0:3]
	s_setprio 0
	s_barrier
	s_add_i32 s82, s82, 2
	s_add_u32 s80, s80, 0x100
	s_addc_u32 s81, s81, 0
	s_add_u32 s60, s60, 0x100
	s_addc_u32 s61, s61, 0
	s_cmp_gt_u32 s82, 5

.LBB0_821:
	s_ashr_i32 s21, s20, 31
	s_lshl_b64 s[48:49], s[20:21], 19
	s_add_u32 s48, s70, s48
	s_addc_u32 s49, s71, s49
	s_and_b64 s[50:51], s[46:47], exec
	s_cselect_b32 s21, s49, s61
	s_cselect_b32 s81, s48, s60
	s_ashr_i32 s19, s18, 31
	s_lshl_b64 s[50:51], s[18:19], 19
	v_readlane_b32 s19, v254, 54
	s_add_u32 s50, s19, s50
	v_readlane_b32 s19, v254, 55
	s_addc_u32 s51, s19, s51
	s_and_b64 s[66:67], s[46:47], exec
	s_cselect_b32 s19, s51, s63
	s_cselect_b32 s82, s50, s62
	s_add_u32 s83, s62, 0x100
	s_addc_u32 s84, s63, 0
	s_add_u32 s60, s60, 0x40080
	s_addc_u32 s61, s61, 0
	s_mov_b32 s85, -2
	s_waitcnt lgkmcnt(0)
	s_add_u32 s62, s60, 0xfffc0080
	s_addc_u32 s63, s61, -1
	s_add_i32 s86, 0, 0x10000
	s_cmp_eq_u32 s85, 12
	s_cselect_b32 s67, s21, s63
	s_cselect_b32 s66, s81, s62
	s_cselect_b32 s63, s19, s84
	s_cselect_b32 s62, s82, s83
	s_add_i32 s89, 0, 0x14000
	v_add_u32_e32 v124, s86, v210
	v_add_u32_e32 v186, s89, v210
	ds_read_b128 v[112:115], v124
	ds_read_b128 v[116:119], v124 offset:1024
	ds_read_b128 v[120:123], v124 offset:2048
	ds_read_b128 v[124:127], v124 offset:3072
	ds_read_b128 v[132:135], v186
	ds_read_b128 v[140:143], v186 offset:1024
	ds_read_b128 v[182:185], v186 offset:2048
	ds_read_b128 v[186:189], v186 offset:3072
	v_lshl_add_u64 v[198:199], s[60:61], 0, v[180:181]
	s_add_i32 m0, s68, 0xc000
	ds_read_b128 v[190:193], v212
	ds_read_b128 v[194:197], v212 offset:1024
	ds_read_b128 v[214:217], v212 offset:2048
	ds_read_b128 v[218:221], v212 offset:3072
	ds_read_b128 v[224:227], v212 offset:4096
	ds_read_b128 v[228:231], v212 offset:5120
	ds_read_b128 v[232:235], v212 offset:6144
	ds_read_b128 v[236:239], v212 offset:7168
	global_load_lds_dwordx4 v[198:199], off
	v_lshl_add_u64 v[198:199], s[60:61], 0, v[178:179]
	s_add_i32 m0, s68, 0xe000
	s_nop 0
	global_load_lds_dwordx4 v[198:199], off
	s_waitcnt vmcnt(8)
	s_waitcnt lgkmcnt(0)
	s_barrier
	s_setprio 1
	s_waitcnt lgkmcnt(0)
	v_mfma_f32_16x16x32_bf16 v[148:151], v[112:115], v[190:193], 0
	v_mfma_f32_16x16x32_bf16 v[144:147], v[120:123], v[190:193], 0
	v_mfma_f32_16x16x32_bf16 v[108:111], v[112:115], v[214:217], 0
	v_mfma_f32_16x16x32_bf16 v[104:107], v[120:123], v[214:217], 0
	v_mfma_f32_16x16x32_bf16 v[92:95], v[112:115], v[224:227], 0
	v_mfma_f32_16x16x32_bf16 v[88:91], v[120:123], v[224:227], 0
	v_mfma_f32_16x16x32_bf16 v[76:79], v[112:115], v[232:235], 0
	v_mfma_f32_16x16x32_bf16 v[72:75], v[120:123], v[232:235], 0
	v_mfma_f32_16x16x32_bf16 v[148:151], v[116:119], v[194:197], v[148:151]
	v_mfma_f32_16x16x32_bf16 v[144:147], v[124:127], v[194:197], v[144:147]
	v_mfma_f32_16x16x32_bf16 v[108:111], v[116:119], v[218:221], v[108:111]
	v_mfma_f32_16x16x32_bf16 v[104:107], v[124:127], v[218:221], v[104:107]
	v_mfma_f32_16x16x32_bf16 v[92:95], v[116:119], v[228:231], v[92:95]
	v_mfma_f32_16x16x32_bf16 v[88:91], v[124:127], v[228:231], v[88:91]
	v_mfma_f32_16x16x32_bf16 v[76:79], v[116:119], v[236:239], v[76:79]
	v_mfma_f32_16x16x32_bf16 v[72:75], v[124:127], v[236:239], v[72:75]
	s_setprio 0
	s_setprio 1
	v_mfma_f32_16x16x32_bf16 v[136:139], v[132:135], v[190:193], 0
	v_mfma_f32_16x16x32_bf16 v[128:131], v[182:185], v[190:193], 0
	v_mfma_f32_16x16x32_bf16 v[100:103], v[132:135], v[214:217], 0
	v_mfma_f32_16x16x32_bf16 v[96:99], v[182:185], v[214:217], 0
	v_mfma_f32_16x16x32_bf16 v[84:87], v[132:135], v[224:227], 0
	v_mfma_f32_16x16x32_bf16 v[80:83], v[182:185], v[224:227], 0
	v_mfma_f32_16x16x32_bf16 v[68:71], v[132:135], v[232:235], 0
	v_mfma_f32_16x16x32_bf16 v[64:67], v[182:185], v[232:235], 0
	v_mfma_f32_16x16x32_bf16 v[136:139], v[140:143], v[194:197], v[136:139]
	v_mfma_f32_16x16x32_bf16 v[128:131], v[186:189], v[194:197], v[128:131]
	v_mfma_f32_16x16x32_bf16 v[100:103], v[140:143], v[218:221], v[100:103]
	v_mfma_f32_16x16x32_bf16 v[96:99], v[186:189], v[218:221], v[96:99]
	v_mfma_f32_16x16x32_bf16 v[84:87], v[140:143], v[228:231], v[84:87]
	v_mfma_f32_16x16x32_bf16 v[80:83], v[186:189], v[228:231], v[80:83]
	v_mfma_f32_16x16x32_bf16 v[68:71], v[140:143], v[236:239], v[68:71]
	v_mfma_f32_16x16x32_bf16 v[64:67], v[186:189], v[236:239], v[64:67]
	s_setprio 0
	s_barrier
	s_add_i32 s86, s86, s59
	v_lshl_add_u64 v[198:199], s[62:63], 0, v[152:153]
	s_mov_b32 m0, s86
	ds_read_b128 v[190:193], v212 offset:16384
	ds_read_b128 v[194:197], v212 offset:17408
	ds_read_b128 v[214:217], v212 offset:18432
	ds_read_b128 v[218:221], v212 offset:19456
	ds_read_b128 v[224:227], v212 offset:20480
	ds_read_b128 v[228:231], v212 offset:21504
	ds_read_b128 v[232:235], v212 offset:22528
	ds_read_b128 v[236:239], v212 offset:23552
	global_load_lds_dwordx4 v[198:199], off
	s_add_i32 m0, s86, 0x2000
	s_add_u32 s86, s62, 0x40000
	v_lshl_add_u64 v[240:241], s[62:63], 0, v[172:173]
	s_addc_u32 s87, s63, 0
	s_add_i32 s89, s89, s59
	global_load_lds_dwordx4 v[240:241], off
	v_lshl_add_u64 v[242:243], s[86:87], 0, v[152:153]
	s_mov_b32 m0, s89
	v_lshl_add_u64 v[244:245], s[66:67], 0, v[174:175]
	global_load_lds_dwordx4 v[242:243], off
	v_lshl_add_u64 v[242:243], s[86:87], 0, v[172:173]
	s_add_i32 m0, s89, 0x2000
	s_nop 0
	global_load_lds_dwordx4 v[242:243], off
	v_lshl_add_u64 v[242:243], s[66:67], 0, v[176:177]
	s_mov_b32 m0, s68
	s_nop 0
	global_load_lds_dwordx4 v[242:243], off
	s_mov_b32 m0, s69
	s_nop 0
	global_load_lds_dwordx4 v[244:245], off
	s_waitcnt vmcnt(8)
	s_waitcnt lgkmcnt(0)
	s_barrier
	s_setprio 1
	s_waitcnt lgkmcnt(0)
	v_mfma_f32_16x16x32_bf16 v[60:63], v[112:115], v[190:193], 0
	v_mfma_f32_16x16x32_bf16 v[56:59], v[120:123], v[190:193], 0
	v_mfma_f32_16x16x32_bf16 v[44:47], v[112:115], v[214:217], 0
	v_mfma_f32_16x16x32_bf16 v[40:43], v[120:123], v[214:217], 0
	v_mfma_f32_16x16x32_bf16 v[28:31], v[112:115], v[224:227], 0
	v_mfma_f32_16x16x32_bf16 v[24:27], v[120:123], v[224:227], 0
	v_mfma_f32_16x16x32_bf16 v[12:15], v[112:115], v[232:235], 0
	v_mfma_f32_16x16x32_bf16 v[8:11], v[120:123], v[232:235], 0
	v_mfma_f32_16x16x32_bf16 v[60:63], v[116:119], v[194:197], v[60:63]
	v_mfma_f32_16x16x32_bf16 v[56:59], v[124:127], v[194:197], v[56:59]
	v_mfma_f32_16x16x32_bf16 v[44:47], v[116:119], v[218:221], v[44:47]
	v_mfma_f32_16x16x32_bf16 v[40:43], v[124:127], v[218:221], v[40:43]
	v_mfma_f32_16x16x32_bf16 v[28:31], v[116:119], v[228:231], v[28:31]
	v_mfma_f32_16x16x32_bf16 v[24:27], v[124:127], v[228:231], v[24:27]
	v_mfma_f32_16x16x32_bf16 v[12:15], v[116:119], v[236:239], v[12:15]
	v_mfma_f32_16x16x32_bf16 v[8:11], v[124:127], v[236:239], v[8:11]
	s_setprio 0
	s_setprio 1
	v_mfma_f32_16x16x32_bf16 v[52:55], v[132:135], v[190:193], 0
	v_mfma_f32_16x16x32_bf16 v[48:51], v[182:185], v[190:193], 0
	v_mfma_f32_16x16x32_bf16 v[36:39], v[132:135], v[214:217], 0
	v_mfma_f32_16x16x32_bf16 v[32:35], v[182:185], v[214:217], 0
	v_mfma_f32_16x16x32_bf16 v[20:23], v[132:135], v[224:227], 0
	v_mfma_f32_16x16x32_bf16 v[16:19], v[182:185], v[224:227], 0
	v_mfma_f32_16x16x32_bf16 v[4:7], v[132:135], v[232:235], 0
	v_mfma_f32_16x16x32_bf16 v[0:3], v[182:185], v[232:235], 0
	v_mfma_f32_16x16x32_bf16 v[52:55], v[140:143], v[194:197], v[52:55]
	v_mfma_f32_16x16x32_bf16 v[48:51], v[186:189], v[194:197], v[48:51]
	v_mfma_f32_16x16x32_bf16 v[36:39], v[140:143], v[218:221], v[36:39]
	v_mfma_f32_16x16x32_bf16 v[32:35], v[186:189], v[218:221], v[32:35]
	v_mfma_f32_16x16x32_bf16 v[20:23], v[140:143], v[228:231], v[20:23]
	v_mfma_f32_16x16x32_bf16 v[16:19], v[186:189], v[228:231], v[16:19]
	v_mfma_f32_16x16x32_bf16 v[4:7], v[140:143], v[236:239], v[4:7]
	v_mfma_f32_16x16x32_bf16 v[0:3], v[186:189], v[236:239], v[0:3]
	s_setprio 0
	s_barrier
	s_add_i32 s86, 0, 0x18000
	s_add_i32 s87, 0, 0x1c000
	v_add_u32_e32 v124, s86, v210
	v_add_u32_e32 v186, s87, v210
	ds_read_b128 v[112:115], v124
	ds_read_b128 v[116:119], v124 offset:1024
	ds_read_b128 v[120:123], v124 offset:2048
	ds_read_b128 v[124:127], v124 offset:3072
	ds_read_b128 v[132:135], v186
	ds_read_b128 v[140:143], v186 offset:1024
	ds_read_b128 v[182:185], v186 offset:2048
	ds_read_b128 v[186:189], v186 offset:3072
	s_add_u32 s66, s66, 0x40000
	s_addc_u32 s67, s67, 0
	s_mov_b32 m0, s74
	v_lshl_add_u64 v[246:247], s[66:67], 0, v[176:177]
	ds_read_b128 v[190:193], v212 offset:32768
	ds_read_b128 v[194:197], v212 offset:33792
	ds_read_b128 v[214:217], v212 offset:34816
	ds_read_b128 v[218:221], v212 offset:35840
	ds_read_b128 v[224:227], v212 offset:36864
	ds_read_b128 v[228:231], v212 offset:37888
	ds_read_b128 v[232:235], v212 offset:38912
	ds_read_b128 v[236:239], v212 offset:39936
	global_load_lds_dwordx4 v[246:247], off
	v_lshl_add_u64 v[246:247], s[66:67], 0, v[174:175]
	s_mov_b32 m0, s75
	s_nop 0
	global_load_lds_dwordx4 v[246:247], off
	s_waitcnt vmcnt(8)
	s_waitcnt lgkmcnt(0)
	s_barrier
	s_setprio 1
	s_waitcnt lgkmcnt(0)
	v_mfma_f32_16x16x32_bf16 v[148:151], v[112:115], v[190:193], v[148:151]
	v_mfma_f32_16x16x32_bf16 v[144:147], v[120:123], v[190:193], v[144:147]
	v_mfma_f32_16x16x32_bf16 v[108:111], v[112:115], v[214:217], v[108:111]
	v_mfma_f32_16x16x32_bf16 v[104:107], v[120:123], v[214:217], v[104:107]
	v_mfma_f32_16x16x32_bf16 v[92:95], v[112:115], v[224:227], v[92:95]
	v_mfma_f32_16x16x32_bf16 v[88:91], v[120:123], v[224:227], v[88:91]
	v_mfma_f32_16x16x32_bf16 v[76:79], v[112:115], v[232:235], v[76:79]
	v_mfma_f32_16x16x32_bf16 v[72:75], v[120:123], v[232:235], v[72:75]
	v_mfma_f32_16x16x32_bf16 v[148:151], v[116:119], v[194:197], v[148:151]
	v_mfma_f32_16x16x32_bf16 v[144:147], v[124:127], v[194:197], v[144:147]
	v_mfma_f32_16x16x32_bf16 v[108:111], v[116:119], v[218:221], v[108:111]
	v_mfma_f32_16x16x32_bf16 v[104:107], v[124:127], v[218:221], v[104:107]
	v_mfma_f32_16x16x32_bf16 v[92:95], v[116:119], v[228:231], v[92:95]
	v_mfma_f32_16x16x32_bf16 v[88:91], v[124:127], v[228:231], v[88:91]
	v_mfma_f32_16x16x32_bf16 v[76:79], v[116:119], v[236:239], v[76:79]
	v_mfma_f32_16x16x32_bf16 v[72:75], v[124:127], v[236:239], v[72:75]
	s_setprio 0
	s_setprio 1
	v_mfma_f32_16x16x32_bf16 v[136:139], v[132:135], v[190:193], v[136:139]
	v_mfma_f32_16x16x32_bf16 v[128:131], v[182:185], v[190:193], v[128:131]
	v_mfma_f32_16x16x32_bf16 v[100:103], v[132:135], v[214:217], v[100:103]
	v_mfma_f32_16x16x32_bf16 v[96:99], v[182:185], v[214:217], v[96:99]
	v_mfma_f32_16x16x32_bf16 v[84:87], v[132:135], v[224:227], v[84:87]
	v_mfma_f32_16x16x32_bf16 v[80:83], v[182:185], v[224:227], v[80:83]
	v_mfma_f32_16x16x32_bf16 v[68:71], v[132:135], v[232:235], v[68:71]
	v_mfma_f32_16x16x32_bf16 v[64:67], v[182:185], v[232:235], v[64:67]
	v_mfma_f32_16x16x32_bf16 v[136:139], v[140:143], v[194:197], v[136:139]
	v_mfma_f32_16x16x32_bf16 v[128:131], v[186:189], v[194:197], v[128:131]
	v_mfma_f32_16x16x32_bf16 v[100:103], v[140:143], v[218:221], v[100:103]
	v_mfma_f32_16x16x32_bf16 v[96:99], v[186:189], v[218:221], v[96:99]
	v_mfma_f32_16x16x32_bf16 v[84:87], v[140:143], v[228:231], v[84:87]
	v_mfma_f32_16x16x32_bf16 v[80:83], v[186:189], v[228:231], v[80:83]
	v_mfma_f32_16x16x32_bf16 v[68:71], v[140:143], v[236:239], v[68:71]
	v_mfma_f32_16x16x32_bf16 v[64:67], v[186:189], v[236:239], v[64:67]
	s_setprio 0
	s_barrier
	s_add_i32 s66, s86, s59
	v_lshl_add_u64 v[198:199], v[198:199], 0, s[22:23]
	s_mov_b32 m0, s66
	ds_read_b128 v[190:193], v212 offset:49152
	ds_read_b128 v[194:197], v212 offset:50176
	ds_read_b128 v[214:217], v212 offset:51200
	ds_read_b128 v[218:221], v212 offset:52224
	ds_read_b128 v[224:227], v212 offset:53248
	ds_read_b128 v[228:231], v212 offset:54272
	ds_read_b128 v[232:235], v212 offset:55296
	ds_read_b128 v[236:239], v212 offset:56320
	global_load_lds_dwordx4 v[198:199], off
	s_add_i32 m0, s66, 0x2000
	s_add_u32 s62, s62, 0x40080
	v_lshl_add_u64 v[198:199], v[240:241], 0, s[22:23]
	s_addc_u32 s63, s63, 0
	s_add_i32 s66, s87, s59
	global_load_lds_dwordx4 v[198:199], off
	v_lshl_add_u64 v[198:199], s[62:63], 0, v[152:153]
	s_mov_b32 m0, s66
	s_nop 0
	global_load_lds_dwordx4 v[198:199], off
	v_lshl_add_u64 v[198:199], s[62:63], 0, v[172:173]
	s_add_i32 m0, s66, 0x2000
	s_nop 0
	global_load_lds_dwordx4 v[198:199], off
	v_lshl_add_u64 v[198:199], v[242:243], 0, s[22:23]
	s_mov_b32 m0, s77
	s_nop 0
	global_load_lds_dwordx4 v[198:199], off
	v_lshl_add_u64 v[198:199], v[244:245], 0, s[22:23]
	s_mov_b32 m0, s78
	s_nop 0
	global_load_lds_dwordx4 v[198:199], off
	s_waitcnt vmcnt(8)
	s_waitcnt lgkmcnt(0)
	s_barrier
	s_setprio 1
	s_waitcnt lgkmcnt(0)
	v_mfma_f32_16x16x32_bf16 v[60:63], v[112:115], v[190:193], v[60:63]
	v_mfma_f32_16x16x32_bf16 v[56:59], v[120:123], v[190:193], v[56:59]
	v_mfma_f32_16x16x32_bf16 v[44:47], v[112:115], v[214:217], v[44:47]
	v_mfma_f32_16x16x32_bf16 v[40:43], v[120:123], v[214:217], v[40:43]
	v_mfma_f32_16x16x32_bf16 v[28:31], v[112:115], v[224:227], v[28:31]
	v_mfma_f32_16x16x32_bf16 v[24:27], v[120:123], v[224:227], v[24:27]
	v_mfma_f32_16x16x32_bf16 v[12:15], v[112:115], v[232:235], v[12:15]
	v_mfma_f32_16x16x32_bf16 v[8:11], v[120:123], v[232:235], v[8:11]
	v_mfma_f32_16x16x32_bf16 v[60:63], v[116:119], v[194:197], v[60:63]
	v_mfma_f32_16x16x32_bf16 v[56:59], v[124:127], v[194:197], v[56:59]
	v_mfma_f32_16x16x32_bf16 v[44:47], v[116:119], v[218:221], v[44:47]
	v_mfma_f32_16x16x32_bf16 v[40:43], v[124:127], v[218:221], v[40:43]
	v_mfma_f32_16x16x32_bf16 v[28:31], v[116:119], v[228:231], v[28:31]
	v_mfma_f32_16x16x32_bf16 v[24:27], v[124:127], v[228:231], v[24:27]
	v_mfma_f32_16x16x32_bf16 v[12:15], v[116:119], v[236:239], v[12:15]
	v_mfma_f32_16x16x32_bf16 v[8:11], v[124:127], v[236:239], v[8:11]
	s_setprio 0
	s_setprio 1
	v_mfma_f32_16x16x32_bf16 v[52:55], v[132:135], v[190:193], v[52:55]
	v_mfma_f32_16x16x32_bf16 v[48:51], v[182:185], v[190:193], v[48:51]
	v_mfma_f32_16x16x32_bf16 v[36:39], v[132:135], v[214:217], v[36:39]
	v_mfma_f32_16x16x32_bf16 v[32:35], v[182:185], v[214:217], v[32:35]
	v_mfma_f32_16x16x32_bf16 v[20:23], v[132:135], v[224:227], v[20:23]
	v_mfma_f32_16x16x32_bf16 v[16:19], v[182:185], v[224:227], v[16:19]
	v_mfma_f32_16x16x32_bf16 v[4:7], v[132:135], v[232:235], v[4:7]
	v_mfma_f32_16x16x32_bf16 v[0:3], v[182:185], v[232:235], v[0:3]
	v_mfma_f32_16x16x32_bf16 v[52:55], v[140:143], v[194:197], v[52:55]
	v_mfma_f32_16x16x32_bf16 v[48:51], v[186:189], v[194:197], v[48:51]
	v_mfma_f32_16x16x32_bf16 v[36:39], v[140:143], v[218:221], v[36:39]
	v_mfma_f32_16x16x32_bf16 v[32:35], v[186:189], v[218:221], v[32:35]
	v_mfma_f32_16x16x32_bf16 v[20:23], v[140:143], v[228:231], v[20:23]
	v_mfma_f32_16x16x32_bf16 v[16:19], v[186:189], v[228:231], v[16:19]
	v_mfma_f32_16x16x32_bf16 v[4:7], v[140:143], v[236:239], v[4:7]
	v_mfma_f32_16x16x32_bf16 v[0:3], v[186:189], v[236:239], v[0:3]
	s_setprio 0
	s_barrier
	s_add_i32 s85, s85, 2
	s_add_u32 s83, s83, 0x100
	s_addc_u32 s84, s84, 0
	s_add_u32 s60, s60, 0x100
	s_addc_u32 s61, s61, 0
	s_cmp_gt_u32 s85, 13
